# DA loops: persistent negM accumulator-init block + SGPR-base (saddr) K/V prefetch loads; MLA loop: K/V staging coordinates hoisted out of the loop into 4 temporarily freed constant VGPRs with saddr lo
# speedup vs baseline: 1.0172x; 1.0172x over previous
; #define WAIT_V0() asm volatile("s_waitcnt vmcnt(0)" ::: "memory")
; __device__ __forceinline__ int v_rd_base(int lane) { return ((lane & 3) << 3) | (((lane >> 2) & 3) << 6) | (((lane >> 4) & 1) << 5) | (((lane >> 5) & 1) << 8); }
; #define V_COORDS(T) do { if constexpr (VC == 2) { const int sr = (T) >> 4, sc = ((T) & 15) * 8; vgo[0] = sr * LDV + sc; vgo[VC - 1] = (32 + sr) * LDV + sc; vlo[0] = v_st<NCB>(sr, sc); vlo[VC - 1] = v_st<NCB>(32 + sr, sc); } \
;     else { const int sr = (T) >> 3, sc = ((T) & 7) * 8; vgo[0] = sr * LDV + sc; vlo[0] = v_st<NCB>(sr, sc); } } while (0)
; #define QKT(P0, P1, BUF) qkt<DQK, QL>(P0, P1, shm + K_OFF + (BUF) * SHM_K, qr, qlds, kofs, negM)
;   const int tidx = ltid(p.wv);
;   constexpr int NCB = DV / 32, KC = DQK / 64, VC = DV / 64, KRS = DQK * 2, CPR = DQK / 8;
;   constexpr int SHM_V = 64 * DV * 2, SHM_K = 64 * DQK * 2, K_OFF = 32768;
;   const int tid = tidx, wid = tid >> 6, lane = tid & 63, r32 = lane & 31, hi = lane >> 5;
;   constexpr int QR = DQK / 16 - QL;
;   bf16x8 qr[QR];
;   char* qlds = shm + 81920 + wid * (QL * 1024) + lane * 16;
; #pragma unroll
;   for (int d0 = 0; d0 < QR; ++d0) qr[d0] = *reinterpret_cast<const bf16x8*>(qlane + d0 * 16);
;   constexpr bool KDMA = DQK > 128;
;   int kgo[KC], klo[KC], vgo[VC], vlo[VC];
;     ...
;   if constexpr (KDMA) {
;   } else {
; #pragma unroll
;     for (int i = 0; i < KC; ++i) { const int c = tid + i * 512, row = c / CPR, cc = c % CPR; kgo[i] = row * LDK + cc * 8; klo[i] = K_OFF + KSWZ(KRS, row, cc * 16); }
;     V_COORDS(tid);
;   }
;   const int vb0 = (int)(uintptr_t)shm + v_rd_base(lane);
;   int kofs[4];
; #pragma unroll
;   for (int b = 0; b < 4; ++b) kofs[b] = (r32 ^ ((r32 >> 3) & 1)) * KRS + ((b * 32 + hi * 16) ^ ((r32 & 7) << 4));
;   bf16x8 ks[KC], vs[VC];
;     ...
;   f32x16 pA0, pA1, pB0, pB1; bf16x8 pa0, pa1, pa2, pa3;
;   __syncthreads();
;   if constexpr (QL > 0) {
; #pragma unroll
;     for (int d0 = 0; d0 < QL; ++d0) *reinterpret_cast<bf16x8*>(qlds + d0 * 1024) = *reinterpret_cast<const bf16x8*>(qlane + (QR + d0) * 16);
;   }
;   int kb = TKEY(0);
;   SLOAD(kb, 0); WAIT_V0(); SWRITE(0); __syncthreads();
;   QKT(pA0, pA1, 0);
;   partialSM<GM>(pA0, pA1, NEEDMASK(kb), kb, L, qpos, hi);
;   if (NT > 1) { SLOAD(TKEY(1), 1); WAIT_V0(); SWRITE(1); }
;   __syncthreads();
.LBB0_322:
	v_mbcnt_lo_u32_b32 v2, -1, 0
	v_mbcnt_hi_u32_b32 v2, -1, v2
	s_mul_i32 s1, s22, s94
	v_or_b32_e32 v0, s97, v2
	s_lshl_b32 s89, s3, 8
	v_ashrrev_i32_e32 v0, 1, v0
	v_and_b32_e32 v1, 31, v2
	s_add_i32 s89, s89, s1
	v_and_b32_e32 v0, 0xffffffe0, v0
	v_add3_u32 v3, v1, s89, v0
	v_mov_b64_e32 v[0:1], s[68:69]
	v_mad_i64_i32 v[0:1], s[20:21], v3, s88, v[0:1]
	s_lshl_b32 s26, s0, 8
	v_lshrrev_b32_e32 v2, 1, v2
	v_lshl_add_u64 v[0:1], v[0:1], 0, s[26:27]
	v_and_b32_e32 v128, 16, v2
	v_lshl_add_u64 v[0:1], v[0:1], 0, v[128:129]
	v_mbcnt_lo_u32_b32 v42, -1, 0
	v_mbcnt_hi_u32_b32 v42, -1, v42
	global_load_dwordx4 v[142:145], v[0:1], off
	global_load_dwordx4 v[138:141], v[0:1], off offset:32
	global_load_dwordx4 v[134:137], v[0:1], off offset:64
	global_load_dwordx4 v[130:133], v[0:1], off offset:96
	v_or_b32_e32 v2, s97, v42
	v_ashrrev_i32_e32 v0, 31, v2
	v_lshrrev_b32_e32 v0, 29, v0
	v_add_u32_e32 v0, v2, v0
	v_ashrrev_i32_e32 v12, 3, v0
	v_and_b32_e32 v0, -8, v0
	v_ashrrev_i32_e32 v14, 4, v2
	v_lshlrev_b32_e32 v15, 3, v42
	s_lshl_b32 s3, s0, 7
	s_mul_i32 s21, s1, 0xc00
	v_sub_u32_e32 v13, v2, v0
	v_and_b32_e32 v0, 0x78, v15
	v_mul_lo_u32 v1, v14, s86
	s_mul_hi_i32 s20, s1, 0xc00
	s_add_u32 s1, s68, s21
	v_or_b32_e32 v0, v1, v0
	v_mul_lo_u32 v1, v12, s86
	s_addc_u32 s22, s69, s20
	v_lshl_add_u32 v2, v13, 3, v1
	s_add_u32 s76, s1, s26
	v_ashrrev_i32_e32 v3, 31, v2
	v_ashrrev_i32_e32 v1, 31, v0
	s_addc_u32 s77, s22, 0
	v_add_u32_e32 v8, 0xc000, v0
	v_lshlrev_b64 v[158:159], 1, v[2:3]
	v_lshlrev_b64 v[160:161], 1, v[0:1]
	v_lshl_add_u64 v[40:41], s[76:77], 0, v[158:159]
	v_lshl_add_u64 v[4:5], s[76:77], 0, v[160:161]
	v_ashrrev_i32_e32 v9, 31, v8
	s_barrier
	global_load_dwordx4 v[0:3], v[40:41], off offset:1024
	s_nop 0
	global_load_dwordx4 v[4:7], v[4:5], off offset:2048
	v_lshlrev_b64 v[162:163], 1, v[8:9]
	v_lshl_add_u64 v[8:9], s[76:77], 0, v[162:163]
	global_load_dwordx4 v[8:11], v[8:9], off offset:2048
	v_and_b32_e32 v18, 0xfffff0, v14
	v_lshlrev_b32_e32 v19, 1, v14
	v_lshrrev_b32_e32 v17, 3, v12
	v_and_or_b32 v18, v19, 8, v18
	v_bitop3_b32 v17, v17, v12, 1 bitop3:0x6c
	v_bitop3_b32 v12, v12, v13, 7 bitop3:0x6c
	v_add_u32_e32 v13, 32, v14
	v_lshrrev_b32_e32 v19, 1, v14
	v_lshrrev_b32_e32 v18, 1, v18
	v_bfe_u32 v15, v15, 5, 2
	v_and_b32_e32 v14, 3, v14
	v_or_b32_e32 v18, v18, v15
	v_and_or_b32 v14, v19, 4, v14
	v_lshlrev_b32_e32 v44, 4, v42
	v_lshlrev_b32_e32 v18, 9, v18
	v_lshlrev_b32_e32 v14, 6, v14
	v_and_b32_e32 v19, 48, v44
	v_or3_b32 v177, v18, v14, v19
	v_and_b32_e32 v18, 0xfffff0, v13
	v_lshlrev_b32_e32 v13, 1, v13
	v_and_or_b32 v13, v13, 8, v18
	v_lshrrev_b32_e32 v13, 1, v13
	v_or_b32_e32 v13, v13, v15
	v_lshlrev_b32_e32 v13, 9, v13
	v_and_b32_e32 v16, 31, v42
	v_or3_b32 v178, v13, v14, v19
	v_lshrrev_b32_e32 v13, 3, v42
	v_bfe_u32 v43, v42, 5, 1
	v_bitop3_b32 v13, v13, v16, 1 bitop3:0x6c
	v_lshlrev_b32_e32 v45, 7, v13
	v_lshlrev_b32_e32 v46, 4, v43
	v_and_b32_e32 v47, 0x70, v44
	v_lshlrev_b32_e32 v13, 7, v17
	v_bitop3_b32 v174, v46, v45, v47 bitop3:0xde
	v_lshl_add_u32 v179, v12, 4, v13
	s_waitcnt vmcnt(0)
	v_mov_b64_e32 v[30:31], s[18:19]
	v_mov_b64_e32 v[28:29], s[16:17]
	v_mov_b64_e32 v[26:27], s[14:15]
	v_mov_b64_e32 v[24:25], s[12:13]
	v_mov_b64_e32 v[22:23], s[10:11]
	v_mov_b64_e32 v[20:21], s[8:9]
	s_waitcnt vmcnt(2)
	ds_write_b128 v179, v[0:3] offset:32768
	s_waitcnt vmcnt(1)
	ds_write_b128 v177, v[4:7]
	s_waitcnt vmcnt(0)
	ds_write_b128 v178, v[8:11]
	s_waitcnt lgkmcnt(0)
	s_barrier
	ds_read_b128 v[32:35], v174 offset:32768
	ds_read_b128 v[36:39], v174 offset:36864
	v_mov_b64_e32 v[18:19], s[6:7]
	v_mov_b64_e32 v[16:17], s[4:5]
	s_mov_b32 s1, 0x30000
	s_add_u32 s78, s76, 0x30800
	s_waitcnt lgkmcnt(1)
	v_mfma_f32_32x32x16_bf16 v[0:15], v[32:35], v[142:145], v[16:31]
	v_or_b32_e32 v32, 32, v46
	v_bitop3_b32 v175, v32, v45, v47 bitop3:0xde
	s_addc_u32 s79, s77, 0
	v_or_b32_e32 v32, 0x60, v46
	v_bitop3_b32 v176, v32, v45, v47 bitop3:0xde
	v_mov_b32_e32 v170, 0
	s_mov_b32 s26, 3
	s_waitcnt lgkmcnt(0)
	v_mfma_f32_32x32x16_bf16 v[64:79], v[36:39], v[142:145], v[16:31]
	s_nop 6
	ds_read_b128 v[16:19], v175 offset:32768
	ds_read_b128 v[20:23], v175 offset:36864
	v_lshl_add_u64 v[24:25], s[78:79], 0, v[160:161]
	v_lshl_add_u64 v[28:29], s[78:79], 0, v[162:163]
	v_and_b32_e32 v37, 0xc0, v44
	s_mov_b32 s36, 0
	v_lshlrev_b32_e32 v171, 2, v43
	v_mov_b32_e32 v39, v170
	s_waitcnt lgkmcnt(1)
	v_mfma_f32_32x32x16_bf16 v[0:15], v[16:19], v[138:141], v[0:15]
	v_or_b32_e32 v16, 64, v46
	v_bitop3_b32 v173, v16, v45, v47 bitop3:0xde
	v_mov_b32_e32 v43, v170
	v_mov_b32_e32 v44, v170
	v_mov_b32_e32 v45, v170
	v_mov_b32_e32 v46, v170
	v_mov_b32_e32 v47, v170
	s_waitcnt lgkmcnt(0)
	v_mfma_f32_32x32x16_bf16 v[64:79], v[20:23], v[138:141], v[64:79]
	ds_read_b128 v[16:19], v173 offset:32768
	ds_read_b128 v[20:23], v173 offset:36864
	v_mov_b32_e32 v48, 0
	v_mov_b32_e32 v49, v170
	v_mov_b32_e32 v50, v170
	v_mov_b32_e32 v51, v170
	v_mov_b32_e32 v52, v170
	v_mov_b32_e32 v53, v170
	s_waitcnt lgkmcnt(1)
	v_mfma_f32_32x32x16_bf16 v[0:15], v[16:19], v[134:137], v[0:15]
	v_add_co_u32_e32 v16, vcc, s1, v40
	s_mov_b32 s1, s27
	s_nop 0
	v_addc_co_u32_e32 v17, vcc, 0, v41, vcc
	global_load_dwordx4 v[16:19], v[16:17], off offset:1024
	s_nop 0
	global_load_dwordx4 v[24:27], v[24:25], off
	ds_read_b128 v[32:35], v176 offset:32768
	global_load_dwordx4 v[28:31], v[28:29], off
	s_waitcnt lgkmcnt(1)
	v_mfma_f32_32x32x16_bf16 v[64:79], v[20:23], v[134:137], v[64:79]
	v_and_b32_e32 v20, 63, v42
	v_lshlrev_b32_e32 v21, 1, v42
	v_lshlrev_b32_e32 v36, 3, v20
	v_and_b32_e32 v38, 32, v21
	ds_read_b128 v[20:23], v176 offset:36864
	s_lshl_b64 s[0:1], s[0:1], 8
	s_add_u32 s0, s21, s0
	s_waitcnt lgkmcnt(1)
; #define WAIT_V0() asm volatile("s_waitcnt vmcnt(0)" ::: "memory")
; #define SBAR() __builtin_amdgcn_sched_barrier(0)
; #define SWRITE(b) do { FRESH_COORDS(); \
;     if constexpr (!KDMA) { _Pragma("unroll") for (int i = 0; i < KC; ++i) *reinterpret_cast<bf16x8*>(shm + (b) * SHM_K + klo[i]) = ks[i]; } \
;     _Pragma("unroll") for (int i = 0; i < VC; ++i) *reinterpret_cast<bf16x8*>(shm + (b) * SHM_V + vlo[i]) = vs[i]; } while (0)
; #define QKT(P0, P1, BUF) qkt<DQK, QL>(P0, P1, shm + K_OFF + (BUF) * SHM_K, qr, qlds, kofs, negM)
; template <int DQK, int QL>
; __device__ __forceinline__ void qkt(f32x16& p0, f32x16& p1, const char* Ks, const bf16x8 (&qr)[DQK / 16 - QL], const char* qlds, const int (&kofs)[4], float negM) {
;   constexpr int QR = DQK / 16 - QL;
; #pragma unroll
;   for (int r = 0; r < 16; ++r) { p0[r] = negM; p1[r] = negM; }
; #pragma unroll
;   for (int d0 = 0; d0 < DQK / 16; ++d0) {
;     const char* kp = Ks + kofs[d0 & 3] + (d0 >> 2) * 128;
;     bf16x8 b0 = *reinterpret_cast<const bf16x8*>(kp);
;     bf16x8 b1 = *reinterpret_cast<const bf16x8*>(kp + 32 * DQK * 2);
;     bf16x8 qf;
;     if constexpr (QL > 0) { if (d0 < QR) qf = qr[d0 < QR ? d0 : 0]; else qf = *reinterpret_cast<const bf16x8*>(qlds + (d0 - QR) * 1024); }
;     else qf = qr[d0];
;     p0 = __builtin_amdgcn_mfma_f32_32x32x16_bf16(b0, qf, p0, 0, 0, 0);
;     p1 = __builtin_amdgcn_mfma_f32_32x32x16_bf16(b1, qf, p1, 0, 0, 0);
;   }
; }
;     ...
;   int kb = TKEY(0);
;   SLOAD(kb, 0); WAIT_V0(); SWRITE(0); __syncthreads();
;   QKT(pA0, pA1, 0);
;   partialSM<GM>(pA0, pA1, NEEDMASK(kb), kb, L, qpos, hi);
;   if (NT > 1) { SLOAD(TKEY(1), 1); WAIT_V0(); SWRITE(1); }
;   __syncthreads();
;   int j = 1;
;   for (; j + 1 < NT; j += 2) {
;     SBAR();
;     if constexpr (ONEP) { finishSM(pA0, pA1, l_reg, pa0, pa1, pa2, pa3); SBAR(); QKT(pB0, pB1, 1); }
;     else { QKT(pB0, pB1, 1); finishSM(pA0, pA1, l_reg, pa0, pa1, pa2, pa3); }
;     SBAR();
;     SLOAD(TKEY(j + 1), 0); SBAR();
;     pv_all<NCB>(o, vb0, pa0, pa1, pa2, pa3);
;     kb = TKEY(j);
;     partialSM<GM>(pB0, pB1, NEEDMASK(kb), kb, L, qpos, hi);
;     __syncthreads(); WAIT_V0(); SWRITE(0);
	v_mfma_f32_32x32x16_bf16 v[0:15], v[32:35], v[130:133], v[0:15]
	s_addc_u32 s1, s20, s1
	v_and_or_b32 v32, v36, 24, v37
	v_and_b32_e32 v33, 0x100, v36
	s_waitcnt vmcnt(0)
	s_add_u32 s0, s64, s0
	v_or3_b32 v172, v32, v38, v33
	s_addc_u32 s1, s65, s1
	s_waitcnt lgkmcnt(0)
	v_mfma_f32_32x32x16_bf16 v[64:79], v[20:23], v[130:133], v[64:79]
	s_nop 3
	v_exp_f32_e32 v165, v0
	v_exp_f32_e32 v167, v1
	v_exp_f32_e32 v157, v2
	v_exp_f32_e32 v166, v3
	v_exp_f32_e32 v155, v4
	v_exp_f32_e32 v164, v5
	v_exp_f32_e32 v154, v6
	v_exp_f32_e32 v156, v7
	v_exp_f32_e32 v151, v8
	v_exp_f32_e32 v153, v9
	v_exp_f32_e32 v149, v10
	v_exp_f32_e32 v152, v11
	v_exp_f32_e32 v147, v12
	v_exp_f32_e32 v150, v13
	v_exp_f32_e32 v146, v14
	v_exp_f32_e32 v148, v15
	v_or_b32_e32 v128, 0x4000, v172
	s_waitcnt vmcnt(2)
	ds_write_b128 v179, v[16:19] offset:40960
	s_waitcnt vmcnt(1)
	ds_write_b128 v177, v[24:27] offset:16384
	s_waitcnt vmcnt(0)
	ds_write_b128 v178, v[28:31] offset:16384
	s_mov_b64 s[80:81], s[0:1]
	v_mov_b32_e32 v0, 0
	v_mov_b32_e32 v1, v170
	v_mov_b32_e32 v2, v170
	v_mov_b32_e32 v3, v170
	v_mov_b32_e32 v4, v170
	v_mov_b32_e32 v5, v170
	v_mov_b32_e32 v6, v170
	v_mov_b32_e32 v7, v170
	v_mov_b32_e32 v8, v170
	v_mov_b32_e32 v9, v170
	v_mov_b32_e32 v10, v170
	v_mov_b32_e32 v11, v170
	v_mov_b32_e32 v12, v170
	v_mov_b32_e32 v13, v170
	v_mov_b32_e32 v14, v170
	v_mov_b32_e32 v15, v170
	v_mov_b32_e32 v16, 0
	v_mov_b32_e32 v17, v170
	v_mov_b32_e32 v18, v170
	v_mov_b32_e32 v19, v170
	v_mov_b32_e32 v20, v170
	v_mov_b32_e32 v21, v170
	v_mov_b32_e32 v22, v170
	v_mov_b32_e32 v23, v170
	v_mov_b32_e32 v24, v170
	v_mov_b32_e32 v25, v170
	v_mov_b32_e32 v26, v170
	v_mov_b32_e32 v27, v170
	v_mov_b32_e32 v28, v170
	v_mov_b32_e32 v29, v170
	v_mov_b32_e32 v30, v170
	v_mov_b32_e32 v31, v170
	v_mov_b32_e32 v32, 0
	v_mov_b32_e32 v33, v170
	v_mov_b32_e32 v34, v170
	v_mov_b32_e32 v35, v170
	v_mov_b32_e32 v36, v170
	v_mov_b32_e32 v37, v170
	v_mov_b32_e32 v38, v170
	v_mov_b32_e32 v40, v170
	v_mov_b32_e32 v41, v170
	v_mov_b32_e32 v42, v170
	v_mov_b32_e32 v54, v170
	v_mov_b32_e32 v55, v170
	v_mov_b32_e32 v56, v170
	v_mov_b32_e32 v57, v170
	v_mov_b32_e32 v58, v170
	v_mov_b32_e32 v59, v170
	v_mov_b32_e32 v60, v170
	v_mov_b32_e32 v61, v170
	v_mov_b32_e32 v62, v170
	v_mov_b32_e32 v63, v170
	v_mov_b64_e32 v[238:239], s[4:5]
	v_mov_b64_e32 v[240:241], s[6:7]
	v_mov_b64_e32 v[242:243], s[8:9]
	v_mov_b64_e32 v[244:245], s[10:11]
	v_mov_b64_e32 v[246:247], s[12:13]
	v_mov_b64_e32 v[248:249], s[14:15]
	v_mov_b64_e32 v[250:251], s[16:17]
	v_mov_b64_e32 v[252:253], s[18:19]
	s_waitcnt lgkmcnt(0)
	s_barrier
.LBB0_323:
	ds_read_b128 v[96:99], v174 offset:40960
	ds_read_b128 v[182:185], v174 offset:45056
	v_exp_f32_e32 v100, v68
	v_exp_f32_e32 v101, v69
	s_waitcnt lgkmcnt(1)
	v_mfma_f32_32x32x16_bf16 v[80:95], v[96:99], v[142:145], v[238:253]
	ds_read_b128 v[96:99], v175 offset:40960
	ds_read_b128 v[186:189], v175 offset:45056
	v_exp_f32_e32 v102, v70
	v_exp_f32_e32 v103, v71
	v_exp_f32_e32 v104, v72
	v_exp_f32_e32 v105, v73
	v_exp_f32_e32 v106, v74
	v_exp_f32_e32 v107, v75
	s_waitcnt lgkmcnt(1)
	v_mfma_f32_32x32x16_bf16 v[80:95], v[96:99], v[138:141], v[80:95]
	ds_read_b128 v[96:99], v173 offset:40960
	ds_read_b128 v[190:193], v173 offset:45056
	v_exp_f32_e32 v108, v76
	v_exp_f32_e32 v109, v77
	v_exp_f32_e32 v110, v78
	v_exp_f32_e32 v79, v79
	s_waitcnt lgkmcnt(1)
	v_mfma_f32_32x32x16_bf16 v[80:95], v[96:99], v[134:137], v[80:95]
	ds_read_b128 v[96:99], v176 offset:40960
	ds_read_b128 v[194:197], v176 offset:45056
	s_waitcnt lgkmcnt(1)
	v_mfma_f32_32x32x16_bf16 v[80:95], v[96:99], v[130:133], v[80:95]
	v_exp_f32_e32 v96, v64
	v_add_f32_e32 v64, 0, v165
	v_add_f32_e32 v64, v167, v64
	v_add_f32_e32 v64, v157, v64
	v_add_f32_e32 v64, v166, v64
	v_add_f32_e32 v64, v155, v64
	v_add_f32_e32 v64, v164, v64
	v_add_f32_e32 v64, v154, v64
	v_add_f32_e32 v64, v156, v64
	v_add_f32_e32 v64, v151, v64
	v_add_f32_e32 v64, v153, v64
	v_add_f32_e32 v64, v149, v64
	v_add_f32_e32 v64, v152, v64
	v_add_f32_e32 v64, v147, v64
	v_exp_f32_e32 v97, v65
	v_add_f32_e32 v64, v150, v64
	v_exp_f32_e32 v98, v66
	v_add_f32_e32 v64, v146, v64
	v_exp_f32_e32 v99, v67
	v_add_f32_e32 v64, v148, v64
	v_add_f32_e32 v64, v96, v64
	v_add_f32_e32 v64, v97, v64
	v_add_f32_e32 v64, v98, v64
	v_add_f32_e32 v64, v99, v64
	v_add_f32_e32 v64, v100, v64
	v_add_f32_e32 v64, v101, v64
	v_add_f32_e32 v64, v102, v64
	v_add_f32_e32 v64, v103, v64
	v_add_f32_e32 v64, v104, v64
	v_add_f32_e32 v64, v105, v64
	v_add_f32_e32 v64, v106, v64
	v_add_f32_e32 v64, v107, v64
	v_add_f32_e32 v64, v108, v64
	v_add_f32_e32 v64, v109, v64
	v_add_f32_e32 v64, v110, v64
	v_add_f32_e32 v180, v79, v64
	v_mov_b32_e32 v181, v180
	s_nop 1
	v_permlane32_swap_b32_e32 v180, v181
	v_cvt_pk_bf16_f32 v64, v165, v167
	v_cvt_pk_bf16_f32 v65, v157, v166
	v_cvt_pk_bf16_f32 v66, v155, v164
	v_cvt_pk_bf16_f32 v67, v154, v156
	v_cvt_pk_bf16_f32 v68, v151, v153
	v_cvt_pk_bf16_f32 v69, v149, v152
	v_cvt_pk_bf16_f32 v70, v147, v150
	v_cvt_pk_bf16_f32 v71, v146, v148
	v_cvt_pk_bf16_f32 v72, v96, v97
	v_cvt_pk_bf16_f32 v73, v98, v99
	v_cvt_pk_bf16_f32 v74, v100, v101
	v_cvt_pk_bf16_f32 v75, v102, v103
	v_cvt_pk_bf16_f32 v76, v104, v105
	v_cvt_pk_bf16_f32 v77, v106, v107
	v_cvt_pk_bf16_f32 v78, v108, v109
	v_cvt_pk_bf16_f32 v79, v110, v79
	s_nop 0
	v_permlane32_swap_b32_e32 v64, v66
	v_permlane32_swap_b32_e32 v65, v67
	v_permlane32_swap_b32_e32 v68, v70
	v_permlane32_swap_b32_e32 v69, v71
	v_permlane32_swap_b32_e32 v72, v74
	v_permlane32_swap_b32_e32 v73, v75
	v_permlane32_swap_b32_e32 v76, v78
	v_permlane32_swap_b32_e32 v77, v79
	v_mfma_f32_32x32x16_bf16 v[96:111], v[182:185], v[142:145], v[238:253]
	v_mfma_f32_32x32x16_bf16 v[96:111], v[186:189], v[138:141], v[96:111]
	s_add_u32 s100, s80, 0x590c000
	s_addc_u32 s101, s81, 0
	global_load_dwordx4 v[146:149], v158, s[100:101] offset:1280
	global_load_dwordx4 v[150:153], v160, s[100:101] offset:2304
	v_mfma_f32_32x32x16_bf16 v[96:111], v[190:193], v[134:137], v[96:111]
	global_load_dwordx4 v[154:157], v162, s[100:101] offset:2304
	s_waitcnt lgkmcnt(0)
; #define WAIT_L0() asm volatile("s_waitcnt lgkmcnt(0)" ::: "memory")
; #define SBAR() __builtin_amdgcn_sched_barrier(0)
; __device__ __forceinline__ int crow(int r, int hi) { return (r & 3) + 8 * (r >> 2) + 4 * hi; }
; template <bool GM>
; __device__ __forceinline__ void partialSM(f32x16& p0, f32x16& p1, bool mask, int kbase, int L, int qpos, int hi) {
;   if (mask) {
; #pragma unroll
;     for (int r = 0; r < 16; ++r) {
;       int k = kbase + crow(r, hi);
;       asm volatile("" : "+v"(k) : "v"(p0[r]));
;       bool ok = k < L;
;       if (GM) ok = ok && (k < 16 || abs(qpos - k) <= 128);
;       p0[r] = ok ? p0[r] : -1e30f;
;       int k2 = k + 32;
;       asm volatile("" : "+v"(k2) : "v"(p1[r]));
;       bool ok2 = k2 < L;
;       if (GM) ok2 = ok2 && (k2 < 16 || abs(qpos - k2) <= 128);
;       p1[r] = ok2 ? p1[r] : -1e30f;
;     }
; template <int NCB, int D0> __device__ __forceinline__ void pv_one(f32x16& od, int vb, bf16x8 pa0, bf16x8 pa1, bf16x8 pa2, bf16x8 pa3) {
;   constexpr int KSTEP = NCB * 1024, HALF = NCB * 512, B0 = D0 * 512;
;   const s16x4 l0 = tr_read<B0>(vb), h0 = tr_read<B0 + HALF>(vb), l1 = tr_read<B0 + KSTEP>(vb), h1 = tr_read<B0 + KSTEP + HALF>(vb);
;   const s16x4 l2 = tr_read<B0 + 2 * KSTEP>(vb), h2 = tr_read<B0 + 2 * KSTEP + HALF>(vb), l3 = tr_read<B0 + 3 * KSTEP>(vb), h3 = tr_read<B0 + 3 * KSTEP + HALF>(vb);
;   WAIT_L0(); SBAR();
;     ...
;   od = __builtin_amdgcn_mfma_f32_32x32x16_bf16(pa0, PK(l0, h0), od, 0, 0, 0);
;   od = __builtin_amdgcn_mfma_f32_32x32x16_bf16(pa1, PK(l1, h1), od, 0, 0, 0);
;   od = __builtin_amdgcn_mfma_f32_32x32x16_bf16(pa2, PK(l2, h2), od, 0, 0, 0);
;   od = __builtin_amdgcn_mfma_f32_32x32x16_bf16(pa3, PK(l3, h3), od, 0, 0, 0);
;     ...
; }
; template <int NCB> __device__ __forceinline__ void pv_all(f32x16 (&o)[NCB], int vb, bf16x8 pa0, bf16x8 pa1, bf16x8 pa2, bf16x8 pa3) {
;   pv_one<NCB, 0>(o[0], vb, pa0, pa1, pa2, pa3); pv_one<NCB, 1>(o[1], vb, pa0, pa1, pa2, pa3);
;   if constexpr (NCB == 4) { pv_one<NCB, 2>(o[2], vb, pa0, pa1, pa2, pa3); pv_one<NCB, 3>(o[3], vb, pa0, pa1, pa2, pa3); }
; }
	v_mfma_f32_32x32x16_bf16 v[96:111], v[194:197], v[130:133], v[96:111]
	ds_read_b64_tr_b16 v[112:113], v172 offset:0
	ds_read_b64_tr_b16 v[114:115], v172 offset:0x800
	ds_read_b64_tr_b16 v[116:117], v172 offset:0x1000
	ds_read_b64_tr_b16 v[118:119], v172 offset:0x1800
	ds_read_b64_tr_b16 v[120:121], v172 offset:0x2000
	ds_read_b64_tr_b16 v[122:123], v172 offset:0x2800
	ds_read_b64_tr_b16 v[124:125], v172 offset:0x3000
	ds_read_b64_tr_b16 v[126:127], v172 offset:0x3800
	s_nop 0
	s_waitcnt lgkmcnt(6)
	v_mfma_f32_32x32x16_bf16 v[0:15], v[64:67], v[112:115], v[0:15]
	ds_read_b64_tr_b16 v[112:113], v172 offset:0x200
	ds_read_b64_tr_b16 v[114:115], v172 offset:0xa00
	s_waitcnt lgkmcnt(6)
	v_mfma_f32_32x32x16_bf16 v[0:15], v[68:71], v[116:119], v[0:15]
	ds_read_b64_tr_b16 v[116:117], v172 offset:0x1200
	ds_read_b64_tr_b16 v[118:119], v172 offset:0x1a00
	s_waitcnt lgkmcnt(6)
	v_mfma_f32_32x32x16_bf16 v[0:15], v[72:75], v[120:123], v[0:15]
	ds_read_b64_tr_b16 v[120:121], v172 offset:0x2200
	ds_read_b64_tr_b16 v[122:123], v172 offset:0x2a00
	s_waitcnt lgkmcnt(6)
	v_mfma_f32_32x32x16_bf16 v[0:15], v[76:79], v[124:127], v[0:15]
	ds_read_b64_tr_b16 v[124:125], v172 offset:0x3200
	ds_read_b64_tr_b16 v[126:127], v172 offset:0x3a00
	s_waitcnt lgkmcnt(6)
	v_mfma_f32_32x32x16_bf16 v[16:31], v[64:67], v[112:115], v[16:31]
	ds_read_b64_tr_b16 v[112:113], v172 offset:0x400
	ds_read_b64_tr_b16 v[114:115], v172 offset:0xc00
	s_waitcnt lgkmcnt(6)
	v_mfma_f32_32x32x16_bf16 v[16:31], v[68:71], v[116:119], v[16:31]
	ds_read_b64_tr_b16 v[116:117], v172 offset:0x1400
	ds_read_b64_tr_b16 v[118:119], v172 offset:0x1c00
	s_waitcnt lgkmcnt(6)
	v_mfma_f32_32x32x16_bf16 v[16:31], v[72:75], v[120:123], v[16:31]
	ds_read_b64_tr_b16 v[120:121], v172 offset:0x2400
	ds_read_b64_tr_b16 v[122:123], v172 offset:0x2c00
	s_waitcnt lgkmcnt(6)
	v_mfma_f32_32x32x16_bf16 v[16:31], v[76:79], v[124:127], v[16:31]
	ds_read_b64_tr_b16 v[124:125], v172 offset:0x3400
	ds_read_b64_tr_b16 v[126:127], v172 offset:0x3c00
	s_waitcnt lgkmcnt(6)
	v_mfma_f32_32x32x16_bf16 v[32:47], v[64:67], v[112:115], v[32:47]
	ds_read_b64_tr_b16 v[112:113], v172 offset:0x600
	ds_read_b64_tr_b16 v[114:115], v172 offset:0xe00
	s_waitcnt lgkmcnt(6)
	v_mfma_f32_32x32x16_bf16 v[32:47], v[68:71], v[116:119], v[32:47]
	ds_read_b64_tr_b16 v[116:117], v172 offset:0x1600
	ds_read_b64_tr_b16 v[118:119], v172 offset:0x1e00
	s_waitcnt lgkmcnt(6)
	v_mfma_f32_32x32x16_bf16 v[32:47], v[72:75], v[120:123], v[32:47]
	ds_read_b64_tr_b16 v[120:121], v172 offset:0x2600
	ds_read_b64_tr_b16 v[122:123], v172 offset:0x2e00
	s_waitcnt lgkmcnt(6)
	v_mfma_f32_32x32x16_bf16 v[32:47], v[76:79], v[124:127], v[32:47]
	ds_read_b64_tr_b16 v[124:125], v172 offset:0x3600
	ds_read_b64_tr_b16 v[126:127], v172 offset:0x3e00
	s_waitcnt lgkmcnt(6)
	v_mfma_f32_32x32x16_bf16 v[48:63], v[64:67], v[112:115], v[48:63]
	s_add_i32 s20, s36, 64
	s_cmp_le_i32 s20, s59
	v_add_u32_e32 v182, s36, v171
	s_waitcnt lgkmcnt(4)
	v_mfma_f32_32x32x16_bf16 v[48:63], v[68:71], v[116:119], v[48:63]
	s_waitcnt lgkmcnt(2)
	v_mfma_f32_32x32x16_bf16 v[48:63], v[72:75], v[120:123], v[48:63]
	s_waitcnt lgkmcnt(0)
	v_mfma_f32_32x32x16_bf16 v[48:63], v[76:79], v[124:127], v[48:63]
	s_cbranch_scc1 .LBB0_325
	v_add_u32_e32 v64, 64, v182
	s_nop 0
	v_cmp_gt_i32_e32 vcc, s94, v64
	v_add_u32_e32 v64, 32, v64
	s_nop 0
	v_cndmask_b32_e32 v80, v233, v80, vcc
	v_cmp_gt_i32_e32 vcc, s94, v64
	v_add_u32_e32 v64, 0x41, v182
	s_nop 0
	v_cndmask_b32_e32 v96, v233, v96, vcc
	v_cmp_gt_i32_e32 vcc, s94, v64
	v_add_u32_e32 v64, 32, v64
	s_nop 0
	v_cndmask_b32_e32 v81, v233, v81, vcc
	v_cmp_gt_i32_e32 vcc, s94, v64
	v_add_u32_e32 v64, 0x42, v182
	s_nop 0
	v_cndmask_b32_e32 v97, v233, v97, vcc
	v_cmp_gt_i32_e32 vcc, s94, v64
	v_add_u32_e32 v64, 32, v64
	s_nop 0
	v_cndmask_b32_e32 v82, v233, v82, vcc
	v_cmp_gt_i32_e32 vcc, s94, v64
	v_add_u32_e32 v64, 0x43, v182
	s_nop 0
	v_cndmask_b32_e32 v98, v233, v98, vcc
	v_cmp_gt_i32_e32 vcc, s94, v64
	v_add_u32_e32 v64, 32, v64
	s_nop 0
	v_cndmask_b32_e32 v83, v233, v83, vcc
	v_cmp_gt_i32_e32 vcc, s94, v64
	v_add_u32_e32 v64, 0x48, v182
	s_nop 0
	v_cndmask_b32_e32 v99, v233, v99, vcc
	v_cmp_gt_i32_e32 vcc, s94, v64
	v_add_u32_e32 v64, 32, v64
	s_nop 0
	v_cndmask_b32_e32 v84, v233, v84, vcc
	v_cmp_gt_i32_e32 vcc, s94, v64
	v_add_u32_e32 v64, 0x49, v182
	s_nop 0
	v_cndmask_b32_e32 v100, v233, v100, vcc
	v_cmp_gt_i32_e32 vcc, s94, v64
	v_add_u32_e32 v64, 32, v64
	s_nop 0
	v_cndmask_b32_e32 v85, v233, v85, vcc
	v_cmp_gt_i32_e32 vcc, s94, v64
	v_add_u32_e32 v64, 0x4a, v182
	s_nop 0
	v_cndmask_b32_e32 v101, v233, v101, vcc
	v_cmp_gt_i32_e32 vcc, s94, v64
	v_add_u32_e32 v64, 32, v64
	s_nop 0
	v_cndmask_b32_e32 v86, v233, v86, vcc
	v_cmp_gt_i32_e32 vcc, s94, v64
	v_add_u32_e32 v64, 0x4b, v182
	s_nop 0
	v_cndmask_b32_e32 v102, v233, v102, vcc
	v_cmp_gt_i32_e32 vcc, s94, v64
	v_add_u32_e32 v64, 32, v64
	s_nop 0
	v_cndmask_b32_e32 v87, v233, v87, vcc
	v_cmp_gt_i32_e32 vcc, s94, v64
	v_add_u32_e32 v64, 0x50, v182
	s_nop 0
	v_cndmask_b32_e32 v103, v233, v103, vcc
	v_cmp_gt_i32_e32 vcc, s94, v64
	v_add_u32_e32 v64, 32, v64
	s_nop 0
	v_cndmask_b32_e32 v88, v233, v88, vcc
	v_cmp_gt_i32_e32 vcc, s94, v64
	v_add_u32_e32 v64, 0x51, v182
	s_nop 0
	v_cndmask_b32_e32 v104, v233, v104, vcc
	v_cmp_gt_i32_e32 vcc, s94, v64
	v_add_u32_e32 v64, 32, v64
	s_nop 0
	v_cndmask_b32_e32 v89, v233, v89, vcc
	v_cmp_gt_i32_e32 vcc, s94, v64
	v_add_u32_e32 v64, 0x52, v182
	s_nop 0
	v_cndmask_b32_e32 v105, v233, v105, vcc
	v_cmp_gt_i32_e32 vcc, s94, v64
	v_add_u32_e32 v64, 32, v64
	s_nop 0
	v_cndmask_b32_e32 v90, v233, v90, vcc
	v_cmp_gt_i32_e32 vcc, s94, v64
	v_add_u32_e32 v64, 0x53, v182
	s_nop 0
	v_cndmask_b32_e32 v106, v233, v106, vcc
	v_cmp_gt_i32_e32 vcc, s94, v64
	v_add_u32_e32 v64, 32, v64
	s_nop 0
	v_cndmask_b32_e32 v91, v233, v91, vcc
	v_cmp_gt_i32_e32 vcc, s94, v64
	v_add_u32_e32 v64, 0x58, v182
	s_nop 0
	v_cndmask_b32_e32 v107, v233, v107, vcc
	v_cmp_gt_i32_e32 vcc, s94, v64
	v_add_u32_e32 v64, 32, v64
	s_nop 0
	v_cndmask_b32_e32 v92, v233, v92, vcc
	v_cmp_gt_i32_e32 vcc, s94, v64
	v_add_u32_e32 v64, 0x59, v182
	s_nop 0
	v_cndmask_b32_e32 v108, v233, v108, vcc
	v_cmp_gt_i32_e32 vcc, s94, v64
	v_add_u32_e32 v64, 32, v64
	s_nop 0
	v_cndmask_b32_e32 v93, v233, v93, vcc
	v_cmp_gt_i32_e32 vcc, s94, v64
	v_add_u32_e32 v64, 0x5a, v182
	s_nop 0
	v_cndmask_b32_e32 v109, v233, v109, vcc
	v_cmp_gt_i32_e32 vcc, s94, v64
	v_add_u32_e32 v64, 32, v64
	s_nop 0
	v_cndmask_b32_e32 v94, v233, v94, vcc
	v_cmp_gt_i32_e32 vcc, s94, v64
	v_add_u32_e32 v64, 0x5b, v182
	s_nop 0
	v_cndmask_b32_e32 v110, v233, v110, vcc
	v_cmp_gt_i32_e32 vcc, s94, v64
	v_add_u32_e32 v64, 32, v64
	s_nop 0
	v_cndmask_b32_e32 v95, v233, v95, vcc
	v_cmp_gt_i32_e32 vcc, s94, v64
	s_nop 1
	v_cndmask_b32_e32 v111, v233, v111, vcc
; #define WAIT_V0() asm volatile("s_waitcnt vmcnt(0)" ::: "memory")
; #define SBAR() __builtin_amdgcn_sched_barrier(0)
; #define SWRITE(b) do { FRESH_COORDS(); \
;     if constexpr (!KDMA) { _Pragma("unroll") for (int i = 0; i < KC; ++i) *reinterpret_cast<bf16x8*>(shm + (b) * SHM_K + klo[i]) = ks[i]; } \
;     _Pragma("unroll") for (int i = 0; i < VC; ++i) *reinterpret_cast<bf16x8*>(shm + (b) * SHM_V + vlo[i]) = vs[i]; } while (0)
; #define QKT(P0, P1, BUF) qkt<DQK, QL>(P0, P1, shm + K_OFF + (BUF) * SHM_K, qr, qlds, kofs, negM)
; template <int DQK, int QL>
; __device__ __forceinline__ void qkt(f32x16& p0, f32x16& p1, const char* Ks, const bf16x8 (&qr)[DQK / 16 - QL], const char* qlds, const int (&kofs)[4], float negM) {
;   constexpr int QR = DQK / 16 - QL;
; #pragma unroll
;   for (int r = 0; r < 16; ++r) { p0[r] = negM; p1[r] = negM; }
; #pragma unroll
;   for (int d0 = 0; d0 < DQK / 16; ++d0) {
;     const char* kp = Ks + kofs[d0 & 3] + (d0 >> 2) * 128;
;     bf16x8 b0 = *reinterpret_cast<const bf16x8*>(kp);
;     bf16x8 b1 = *reinterpret_cast<const bf16x8*>(kp + 32 * DQK * 2);
;     bf16x8 qf;
;     if constexpr (QL > 0) { if (d0 < QR) qf = qr[d0 < QR ? d0 : 0]; else qf = *reinterpret_cast<const bf16x8*>(qlds + (d0 - QR) * 1024); }
;     else qf = qr[d0];
;     p0 = __builtin_amdgcn_mfma_f32_32x32x16_bf16(b0, qf, p0, 0, 0, 0);
;     p1 = __builtin_amdgcn_mfma_f32_32x32x16_bf16(b1, qf, p1, 0, 0, 0);
;   }
; }
;     ...
;     partialSM<GM>(pB0, pB1, NEEDMASK(kb), kb, L, qpos, hi);
;     __syncthreads(); WAIT_V0(); SWRITE(0);
;     __syncthreads();
;     SBAR();
;     if constexpr (ONEP) { finishSM(pB0, pB1, l_reg, pa0, pa1, pa2, pa3); SBAR(); QKT(pA0, pA1, 0); }
;     else { QKT(pA0, pA1, 0); finishSM(pB0, pB1, l_reg, pa0, pa1, pa2, pa3); }
;     SBAR();
;     if (j + 2 < NT) SLOAD(TKEY(j + 2), 1);
.LBB0_325:
	s_barrier
	s_waitcnt vmcnt(0)
	s_waitcnt vmcnt(2)
	ds_write_b128 v179, v[146:149] offset:32768
	s_waitcnt vmcnt(1)
	ds_write_b128 v177, v[150:153]
	s_waitcnt vmcnt(0)
	ds_write_b128 v178, v[154:157]
	v_exp_f32_e32 v183, v80
	v_exp_f32_e32 v188, v81
	v_exp_f32_e32 v189, v82
	v_exp_f32_e32 v190, v83
	v_exp_f32_e32 v191, v84
	v_exp_f32_e32 v192, v85
	v_exp_f32_e32 v193, v86
	v_exp_f32_e32 v194, v87
	v_exp_f32_e32 v195, v88
	v_exp_f32_e32 v196, v89
	v_exp_f32_e32 v197, v90
	v_exp_f32_e32 v198, v91
	v_exp_f32_e32 v199, v92
	v_exp_f32_e32 v200, v93
	v_exp_f32_e32 v201, v94
	v_exp_f32_e32 v202, v95
	s_waitcnt lgkmcnt(0)
	s_barrier
	ds_read_b128 v[64:67], v174 offset:32768
	ds_read_b128 v[184:187], v174 offset:36864
	v_exp_f32_e32 v111, v111
	s_waitcnt lgkmcnt(1)
	v_mfma_f32_32x32x16_bf16 v[80:95], v[64:67], v[142:145], v[238:253]
	s_waitcnt lgkmcnt(0)
	v_mfma_f32_32x32x16_bf16 v[64:79], v[184:187], v[142:145], v[238:253]
	ds_read_b128 v[112:115], v175 offset:32768
	ds_read_b128 v[116:119], v175 offset:36864
	v_exp_f32_e32 v120, v102
	v_exp_f32_e32 v121, v103
	v_exp_f32_e32 v122, v104
	v_exp_f32_e32 v123, v105
	v_exp_f32_e32 v124, v106
	v_exp_f32_e32 v125, v107
	s_waitcnt lgkmcnt(1)
	v_mfma_f32_32x32x16_bf16 v[80:95], v[112:115], v[138:141], v[80:95]
	v_exp_f32_e32 v126, v108
	v_exp_f32_e32 v127, v109
	v_exp_f32_e32 v184, v110
	s_waitcnt lgkmcnt(0)
	v_mfma_f32_32x32x16_bf16 v[64:79], v[116:119], v[138:141], v[64:79]
	ds_read_b128 v[112:115], v173 offset:32768
	ds_read_b128 v[116:119], v173 offset:36864
	s_waitcnt lgkmcnt(1)
	v_mfma_f32_32x32x16_bf16 v[80:95], v[112:115], v[134:137], v[80:95]
	s_waitcnt lgkmcnt(0)
	v_mfma_f32_32x32x16_bf16 v[64:79], v[116:119], v[134:137], v[64:79]
	ds_read_b128 v[112:115], v176 offset:32768
	ds_read_b128 v[116:119], v176 offset:36864
	s_waitcnt lgkmcnt(1)
	v_mfma_f32_32x32x16_bf16 v[80:95], v[112:115], v[130:133], v[80:95]
	v_exp_f32_e32 v114, v96
	v_add_f32_e32 v96, 0, v183
	v_add_f32_e32 v96, v188, v96
	v_add_f32_e32 v96, v189, v96
	v_add_f32_e32 v96, v190, v96
	v_add_f32_e32 v96, v191, v96
	v_add_f32_e32 v96, v192, v96
	v_add_f32_e32 v96, v193, v96
	v_add_f32_e32 v96, v194, v96
	v_add_f32_e32 v96, v195, v96
	v_add_f32_e32 v96, v196, v96
	v_add_f32_e32 v96, v197, v96
	v_add_f32_e32 v96, v198, v96
	v_add_f32_e32 v96, v199, v96
	v_exp_f32_e32 v115, v97
	v_add_f32_e32 v96, v200, v96
	s_waitcnt lgkmcnt(0)
	v_mfma_f32_32x32x16_bf16 v[64:79], v[116:119], v[130:133], v[64:79]
	v_exp_f32_e32 v116, v98
	v_add_f32_e32 v96, v201, v96
	v_exp_f32_e32 v117, v99
	v_add_f32_e32 v96, v202, v96
	v_exp_f32_e32 v118, v100
	v_add_f32_e32 v96, v114, v96
	v_exp_f32_e32 v119, v101
	v_add_f32_e32 v96, v115, v96
	v_add_f32_e32 v96, v116, v96
	v_add_f32_e32 v96, v117, v96
	v_add_f32_e32 v96, v118, v96
	v_add_f32_e32 v96, v119, v96
	v_add_f32_e32 v96, v120, v96
	v_add_f32_e32 v96, v121, v96
	v_add_f32_e32 v96, v122, v96
	v_add_f32_e32 v96, v123, v96
	v_add_f32_e32 v96, v124, v96
	v_add_f32_e32 v96, v125, v96
	v_add_f32_e32 v96, v126, v96
	v_add_f32_e32 v96, v127, v96
	v_add_f32_e32 v96, v184, v96
	v_add_f32_e32 v112, v111, v96
	v_mov_b32_e32 v113, v112
	v_cvt_pk_bf16_f32 v96, v183, v188
	v_cvt_pk_bf16_f32 v97, v189, v190
	v_cvt_pk_bf16_f32 v98, v191, v192
	v_cvt_pk_bf16_f32 v99, v193, v194
	v_cvt_pk_bf16_f32 v100, v195, v196
	v_cvt_pk_bf16_f32 v101, v197, v198
	v_cvt_pk_bf16_f32 v102, v199, v200
	v_cvt_pk_bf16_f32 v103, v201, v202
	v_cvt_pk_bf16_f32 v104, v114, v115
	v_cvt_pk_bf16_f32 v105, v116, v117
	v_cvt_pk_bf16_f32 v106, v118, v119
	v_cvt_pk_bf16_f32 v107, v120, v121
	v_cvt_pk_bf16_f32 v108, v122, v123
	v_cvt_pk_bf16_f32 v109, v124, v125
	v_cvt_pk_bf16_f32 v110, v126, v127
	v_cvt_pk_bf16_f32 v111, v184, v111
	s_nop 1
	v_permlane32_swap_b32_e32 v112, v113
	v_permlane32_swap_b32_e32 v96, v98
	v_permlane32_swap_b32_e32 v97, v99
	v_permlane32_swap_b32_e32 v100, v102
	v_permlane32_swap_b32_e32 v101, v103
	v_permlane32_swap_b32_e32 v104, v106
	v_permlane32_swap_b32_e32 v105, v107
	v_permlane32_swap_b32_e32 v108, v110
	v_permlane32_swap_b32_e32 v109, v111
	s_cmp_lt_u32 s26, s58
	s_cselect_b64 s[22:23], -1, 0
	s_cmp_ge_u32 s26, s58
	s_cselect_b64 s[20:21], -1, 0
	s_and_b64 vcc, exec, s[20:21]
	s_cbranch_vccnz .LBB0_327
	s_add_u32 s100, s80, 0x593c000
	s_addc_u32 s101, s81, 0
	global_load_dwordx4 v[146:149], v158, s[100:101] offset:1280
	global_load_dwordx4 v[150:153], v160, s[100:101] offset:2304
	global_load_dwordx4 v[154:157], v162, s[100:101] offset:2304

; #define WAIT_L0() asm volatile("s_waitcnt lgkmcnt(0)" ::: "memory")
; __device__ __forceinline__ int crow(int r, int hi) { return (r & 3) + 8 * (r >> 2) + 4 * hi; }
; __device__ __forceinline__ void row_rli(float l_reg, int wid, int r32, int hi, float (&rli)[16]) {
;   float* li_l = (float*)(shm + 155648) + wid * 64;
;   if (hi == 0) li_l[r32] = l_reg;
;   WAIT_L0();
; #pragma unroll
;   for (int r = 0; r < 16; ++r) rli[r] = __builtin_amdgcn_rcpf(li_l[crow(r, hi)]);
; }
; __device__ __forceinline__ void attn_da_full(const Ctx& p, int layer, int hf, int it0) {
;     ...
;       row_rli(l_reg, wid, r32, hi, rli);
;       u32x4* park = (u32x4*)(shm + 65536);
; #pragma unroll
;       for (int d = 0; d < 4; ++d)
; #pragma unroll
;         for (int q = 0; q < 2; ++q) {
;           u32x4 w;
; #pragma unroll
;           for (int e = 0; e < 4; ++e) { const int r = q * 8 + e * 2; w[e] = cvtpk(o[d][r] * rli[r], o[d][r + 1] * rli[r + 1]); }
;           park[(d * 2 + q) * 512 + tidx] = w;
;         }
;     }
; #pragma unroll
;     for (int d = 0; d < 4; ++d)
; #pragma unroll
;       for (int r = 0; r < 16; ++r) o[d][r] = 0.f;
;     l_reg = 0.f;
;     {
;       const int tidx = ltid(p.wv), wid = tidx >> 6, lane = tidx & 63, r32 = lane & 31, hi = lane >> 5;
;       const int lrow = sb + qt * 256 + wid * 32 + r32;
;       attn_body<64, 128, 1536, 1536, false>(p, DA + (size_t)lrow * 1536 + (h * 2 + 1) * 64 + hi * 8, DA + (size_t)sb * 1536 + 512 + (h * 2 + 1) * 64,
.LBB0_339:
	v_mbcnt_lo_u32_b32 v3, -1, 0
	v_mbcnt_hi_u32_b32 v3, -1, v3
	s_nop 0
	v_or_b32_e32 v0, s97, v3
	v_lshlrev_b32_e32 v2, 2, v0
	v_bfe_u32 v1, v3, 5, 1
	v_and_b32_e32 v2, 0xffffff00, v2
	v_add_u32_e32 v2, 0x26000, v2
	v_cmp_eq_u32_e32 vcc, 0, v1
	s_and_saveexec_b64 s[20:21], vcc
	v_and_b32_e32 v3, 31, v3
	v_lshl_add_u32 v3, v3, 2, v2
	ds_write_b32 v3, v158
	s_or_b64 exec, exec, s[20:21]
	s_waitcnt lgkmcnt(0)
	v_lshl_add_u32 v1, v1, 4, v2
	ds_read_b128 v[2:5], v1
	ds_read_b128 v[6:9], v1 offset:32
	s_lshl_b32 s26, s3, 1
	s_mov_b32 s3, 0x30000
	v_mov_b32_e32 v170, 0
	s_waitcnt lgkmcnt(1)
	v_rcp_f32_e32 v10, v2
	v_rcp_f32_e32 v11, v3
	v_rcp_f32_e32 v12, v4
	v_rcp_f32_e32 v13, v5
	ds_read_b128 v[2:5], v1 offset:64
	s_waitcnt lgkmcnt(1)
	v_rcp_f32_e32 v14, v6
	v_rcp_f32_e32 v15, v7
	v_rcp_f32_e32 v16, v8
	v_rcp_f32_e32 v17, v9
	ds_read_b128 v[6:9], v1 offset:96
	v_mov_b32_e32 v1, 0x10000
	s_waitcnt lgkmcnt(1)
	v_rcp_f32_e32 v18, v2
	v_rcp_f32_e32 v19, v3
	v_lshl_add_u32 v20, v0, 4, v1
	v_mul_f32_e32 v0, v64, v10
	v_mul_f32_e32 v1, v65, v11
	v_rcp_f32_e32 v4, v4
	v_rcp_f32_e32 v5, v5
	v_cvt_pk_bf16_f32 v0, v0, v1
	v_mul_f32_e32 v1, v66, v12
	v_mul_f32_e32 v2, v67, v13
	s_waitcnt lgkmcnt(0)
	v_rcp_f32_e32 v6, v6
	v_rcp_f32_e32 v7, v7
	v_cvt_pk_bf16_f32 v1, v1, v2
	v_mul_f32_e32 v2, v68, v14
	v_mul_f32_e32 v3, v69, v15
	v_rcp_f32_e32 v8, v8
	v_cvt_pk_bf16_f32 v2, v2, v3
	v_mul_f32_e32 v3, v70, v16
	v_rcp_f32_e32 v9, v9
	v_mul_f32_e32 v21, v71, v17
	v_cvt_pk_bf16_f32 v3, v3, v21
	ds_write_b128 v20, v[0:3]
	v_mul_f32_e32 v0, v72, v18
	v_mul_f32_e32 v1, v73, v19
	v_cvt_pk_bf16_f32 v0, v0, v1
	v_mul_f32_e32 v1, v74, v4
	v_mul_f32_e32 v2, v75, v5
	v_cvt_pk_bf16_f32 v1, v1, v2
	v_mul_f32_e32 v2, v76, v6
	v_mul_f32_e32 v3, v77, v7
	v_cvt_pk_bf16_f32 v2, v2, v3
	v_mul_f32_e32 v3, v78, v8
	v_mul_f32_e32 v21, v79, v9
	v_cvt_pk_bf16_f32 v3, v3, v21
	ds_write_b128 v20, v[0:3] offset:8192
	v_mul_f32_e32 v0, v80, v10
	v_mul_f32_e32 v1, v81, v11
	v_cvt_pk_bf16_f32 v0, v0, v1
	v_mul_f32_e32 v1, v82, v12
	v_mul_f32_e32 v2, v83, v13
	v_cvt_pk_bf16_f32 v1, v1, v2
	v_mul_f32_e32 v2, v84, v14
	v_mul_f32_e32 v3, v85, v15
	v_cvt_pk_bf16_f32 v2, v2, v3
	v_mul_f32_e32 v3, v86, v16
	v_mul_f32_e32 v21, v87, v17
	v_cvt_pk_bf16_f32 v3, v3, v21
	ds_write_b128 v20, v[0:3] offset:16384
	v_mul_f32_e32 v0, v88, v18
	v_mul_f32_e32 v1, v89, v19
	v_cvt_pk_bf16_f32 v0, v0, v1
	v_mul_f32_e32 v1, v90, v4
	v_mul_f32_e32 v2, v91, v5
	v_cvt_pk_bf16_f32 v1, v1, v2
	v_mul_f32_e32 v2, v92, v6
	v_mul_f32_e32 v3, v93, v7
	v_cvt_pk_bf16_f32 v2, v2, v3
	v_mul_f32_e32 v3, v94, v8
	v_mul_f32_e32 v21, v95, v9
	v_cvt_pk_bf16_f32 v3, v3, v21
	ds_write_b128 v20, v[0:3] offset:24576
	v_mul_f32_e32 v0, v96, v10
	v_mul_f32_e32 v1, v97, v11
	v_cvt_pk_bf16_f32 v0, v0, v1
	v_mul_f32_e32 v1, v98, v12
	v_mul_f32_e32 v2, v99, v13
	v_cvt_pk_bf16_f32 v1, v1, v2
	v_mul_f32_e32 v2, v100, v14
	v_mul_f32_e32 v3, v101, v15
	v_cvt_pk_bf16_f32 v2, v2, v3
	v_mul_f32_e32 v3, v102, v16
	v_mul_f32_e32 v21, v103, v17
	v_cvt_pk_bf16_f32 v3, v3, v21
	ds_write_b128 v20, v[0:3] offset:32768
	v_mul_f32_e32 v0, v104, v18
	v_mul_f32_e32 v1, v105, v19
	v_cvt_pk_bf16_f32 v0, v0, v1
	v_mul_f32_e32 v1, v106, v4
	v_mul_f32_e32 v2, v107, v5
	v_cvt_pk_bf16_f32 v1, v1, v2
	v_mul_f32_e32 v2, v108, v6
	v_mul_f32_e32 v3, v109, v7
	v_cvt_pk_bf16_f32 v2, v2, v3
	v_mul_f32_e32 v3, v110, v8
	v_mul_f32_e32 v21, v111, v9
	v_cvt_pk_bf16_f32 v3, v3, v21
	ds_write_b128 v20, v[0:3] offset:40960
	v_mul_f32_e32 v0, v112, v10
	v_mul_f32_e32 v1, v113, v11
	v_cvt_pk_bf16_f32 v0, v0, v1
	v_mul_f32_e32 v1, v114, v12
	v_mul_f32_e32 v2, v115, v13
	v_cvt_pk_bf16_f32 v1, v1, v2
	v_mul_f32_e32 v2, v116, v14
	v_mul_f32_e32 v3, v117, v15
	v_cvt_pk_bf16_f32 v2, v2, v3
	v_mul_f32_e32 v3, v118, v16
	v_mul_f32_e32 v10, v119, v17
	v_cvt_pk_bf16_f32 v3, v3, v10
	ds_write_b128 v20, v[0:3] offset:49152
	v_mul_f32_e32 v0, v120, v18
	v_mul_f32_e32 v1, v121, v19
	v_cvt_pk_bf16_f32 v0, v0, v1
	v_mul_f32_e32 v1, v122, v4
	v_mul_f32_e32 v2, v123, v5
	v_cvt_pk_bf16_f32 v1, v1, v2
	v_mul_f32_e32 v2, v124, v6
	v_mul_f32_e32 v3, v125, v7
	v_cvt_pk_bf16_f32 v2, v2, v3
	v_mul_f32_e32 v3, v126, v8
	v_mul_f32_e32 v4, v127, v9
	v_cvt_pk_bf16_f32 v3, v3, v4
	ds_write_b128 v20, v[0:3] offset:57344
	v_mbcnt_lo_u32_b32 v2, -1, 0
	v_mbcnt_hi_u32_b32 v2, -1, v2
	v_mbcnt_lo_u32_b32 v42, -1, 0
	v_mbcnt_hi_u32_b32 v42, -1, v42
	s_mov_b32 s36, 0
	v_or_b32_e32 v0, s97, v2
	v_ashrrev_i32_e32 v0, 1, v0
	v_and_b32_e32 v1, 31, v2
	v_and_b32_e32 v0, 0xffffffe0, v0
	v_add3_u32 v3, v1, s89, v0
	v_mov_b64_e32 v[0:1], s[68:69]
	v_mad_i64_i32 v[0:1], s[20:21], v3, s88, v[0:1]
	v_lshrrev_b32_e32 v2, 1, v2
	v_lshl_add_u64 v[0:1], v[0:1], 0, s[26:27]
	v_and_b32_e32 v128, 16, v2
	v_lshl_add_u64 v[0:1], v[0:1], 0, v[128:129]
	v_or_b32_e32 v2, s97, v42
	global_load_dwordx4 v[142:145], v[0:1], off offset:128
	global_load_dwordx4 v[138:141], v[0:1], off offset:160
	global_load_dwordx4 v[134:137], v[0:1], off offset:192
	global_load_dwordx4 v[130:133], v[0:1], off offset:224
	v_ashrrev_i32_e32 v0, 31, v2
	v_lshrrev_b32_e32 v0, 29, v0
	v_add_u32_e32 v0, v2, v0
	v_ashrrev_i32_e32 v12, 3, v0
	v_and_b32_e32 v0, -8, v0
	v_ashrrev_i32_e32 v14, 4, v2
	v_lshlrev_b32_e32 v15, 3, v42
	v_sub_u32_e32 v13, v2, v0
	v_and_b32_e32 v0, 0x78, v15
	v_mul_lo_u32 v1, v14, s86
	v_or_b32_e32 v0, v1, v0
	v_mul_lo_u32 v1, v12, s86
	v_lshl_add_u32 v2, v13, 3, v1
	v_ashrrev_i32_e32 v3, 31, v2
	v_ashrrev_i32_e32 v1, 31, v0
	v_add_u32_e32 v8, 0xc000, v0
	v_lshlrev_b64 v[158:159], 1, v[2:3]
	v_lshlrev_b64 v[160:161], 1, v[0:1]
	v_lshl_add_u64 v[40:41], s[76:77], 0, v[158:159]
	v_lshl_add_u64 v[4:5], s[76:77], 0, v[160:161]
	v_ashrrev_i32_e32 v9, 31, v8
	s_waitcnt lgkmcnt(0)
	s_barrier
; #define WAIT_V0() asm volatile("s_waitcnt vmcnt(0)" ::: "memory")
; __device__ __forceinline__ int v_rd_base(int lane) { return ((lane & 3) << 3) | (((lane >> 2) & 3) << 6) | (((lane >> 4) & 1) << 5) | (((lane >> 5) & 1) << 8); }
; #define V_COORDS(T) do { if constexpr (VC == 2) { const int sr = (T) >> 4, sc = ((T) & 15) * 8; vgo[0] = sr * LDV + sc; vgo[VC - 1] = (32 + sr) * LDV + sc; vlo[0] = v_st<NCB>(sr, sc); vlo[VC - 1] = v_st<NCB>(32 + sr, sc); } \
;     else { const int sr = (T) >> 3, sc = ((T) & 7) * 8; vgo[0] = sr * LDV + sc; vlo[0] = v_st<NCB>(sr, sc); } } while (0)
; #define SWRITE(b) do { FRESH_COORDS(); \
;     if constexpr (!KDMA) { _Pragma("unroll") for (int i = 0; i < KC; ++i) *reinterpret_cast<bf16x8*>(shm + (b) * SHM_K + klo[i]) = ks[i]; } \
;     _Pragma("unroll") for (int i = 0; i < VC; ++i) *reinterpret_cast<bf16x8*>(shm + (b) * SHM_V + vlo[i]) = vs[i]; } while (0)
;     ...
;   const int tid = tidx, wid = tid >> 6, lane = tid & 63, r32 = lane & 31, hi = lane >> 5;
;   constexpr int QR = DQK / 16 - QL;
;   bf16x8 qr[QR];
;   char* qlds = shm + 81920 + wid * (QL * 1024) + lane * 16;
; #pragma unroll
;   for (int d0 = 0; d0 < QR; ++d0) qr[d0] = *reinterpret_cast<const bf16x8*>(qlane + d0 * 16);
;   constexpr bool KDMA = DQK > 128;
;   int kgo[KC], klo[KC], vgo[VC], vlo[VC];
;     ...
;   if constexpr (KDMA) {
;   } else {
; #pragma unroll
;     for (int i = 0; i < KC; ++i) { const int c = tid + i * 512, row = c / CPR, cc = c % CPR; kgo[i] = row * LDK + cc * 8; klo[i] = K_OFF + KSWZ(KRS, row, cc * 16); }
;     V_COORDS(tid);
;   }
;   const int vb0 = (int)(uintptr_t)shm + v_rd_base(lane);
;   int kofs[4];
; #pragma unroll
;   for (int b = 0; b < 4; ++b) kofs[b] = (r32 ^ ((r32 >> 3) & 1)) * KRS + ((b * 32 + hi * 16) ^ ((r32 & 7) << 4));
;   bf16x8 ks[KC], vs[VC];
;     ...
;   f32x16 pA0, pA1, pB0, pB1; bf16x8 pa0, pa1, pa2, pa3;
;   __syncthreads();
;   if constexpr (QL > 0) {
; #pragma unroll
;     for (int d0 = 0; d0 < QL; ++d0) *reinterpret_cast<bf16x8*>(qlds + d0 * 1024) = *reinterpret_cast<const bf16x8*>(qlane + (QR + d0) * 16);
;   }
;   int kb = TKEY(0);
;   SLOAD(kb, 0); WAIT_V0(); SWRITE(0); __syncthreads();
;   QKT(pA0, pA1, 0);
;   partialSM<GM>(pA0, pA1, NEEDMASK(kb), kb, L, qpos, hi);
;   if (NT > 1) { SLOAD(TKEY(1), 1); WAIT_V0(); SWRITE(1); }
;   __syncthreads();
	global_load_dwordx4 v[0:3], v[40:41], off offset:1152
	s_nop 0
	global_load_dwordx4 v[4:7], v[4:5], off offset:2048
	v_lshlrev_b64 v[162:163], 1, v[8:9]
	v_lshl_add_u64 v[8:9], s[76:77], 0, v[162:163]
	global_load_dwordx4 v[8:11], v[8:9], off offset:2048
	v_and_b32_e32 v18, 0xfffff0, v14
	v_lshlrev_b32_e32 v19, 1, v14
	v_lshrrev_b32_e32 v17, 3, v12
	v_and_or_b32 v18, v19, 8, v18
	v_bitop3_b32 v17, v17, v12, 1 bitop3:0x6c
	v_bitop3_b32 v12, v12, v13, 7 bitop3:0x6c
	v_add_u32_e32 v13, 32, v14
	v_lshrrev_b32_e32 v19, 1, v14
	v_lshrrev_b32_e32 v18, 1, v18
	v_bfe_u32 v15, v15, 5, 2
	v_and_b32_e32 v14, 3, v14
	v_or_b32_e32 v18, v18, v15
	v_and_or_b32 v14, v19, 4, v14
	v_lshlrev_b32_e32 v44, 4, v42
	v_lshlrev_b32_e32 v18, 9, v18
	v_lshlrev_b32_e32 v14, 6, v14
	v_and_b32_e32 v19, 48, v44
	v_or3_b32 v177, v18, v14, v19
	v_and_b32_e32 v18, 0xfffff0, v13
	v_lshlrev_b32_e32 v13, 1, v13
	v_and_or_b32 v13, v13, 8, v18
	v_lshrrev_b32_e32 v13, 1, v13
	v_or_b32_e32 v13, v13, v15
	v_lshlrev_b32_e32 v13, 9, v13
	v_and_b32_e32 v16, 31, v42
	v_or3_b32 v178, v13, v14, v19
	v_lshrrev_b32_e32 v13, 3, v42
	v_bfe_u32 v43, v42, 5, 1
	v_bitop3_b32 v13, v13, v16, 1 bitop3:0x6c
	v_lshlrev_b32_e32 v45, 7, v13
	v_lshlrev_b32_e32 v46, 4, v43
	v_and_b32_e32 v47, 0x70, v44
	v_lshlrev_b32_e32 v13, 7, v17
	v_bitop3_b32 v174, v46, v45, v47 bitop3:0xde
	v_lshl_add_u32 v179, v12, 4, v13
	s_waitcnt vmcnt(0)
	s_waitcnt vmcnt(2)
	ds_write_b128 v179, v[0:3] offset:32768
	s_waitcnt vmcnt(1)
	ds_write_b128 v177, v[4:7]
	s_waitcnt vmcnt(0)
	ds_write_b128 v178, v[8:11]
	s_waitcnt lgkmcnt(0)
	s_barrier
	ds_read_b128 v[32:35], v174 offset:32768
	ds_read_b128 v[36:39], v174 offset:36864
	v_mov_b64_e32 v[30:31], s[18:19]
	v_mov_b64_e32 v[28:29], s[16:17]
	v_mov_b64_e32 v[26:27], s[14:15]
	v_mov_b64_e32 v[24:25], s[12:13]
	v_mov_b64_e32 v[22:23], s[10:11]
	v_mov_b64_e32 v[20:21], s[8:9]
	v_mov_b64_e32 v[18:19], s[6:7]
	v_mov_b64_e32 v[16:17], s[4:5]
	v_lshlrev_b32_e32 v171, 2, v43
	v_mov_b32_e32 v43, v170
	s_waitcnt lgkmcnt(1)
	v_mfma_f32_32x32x16_bf16 v[0:15], v[32:35], v[142:145], v[16:31]
	v_or_b32_e32 v32, 32, v46
	v_bitop3_b32 v175, v32, v45, v47 bitop3:0xde
	v_or_b32_e32 v32, 0x60, v46
	v_bitop3_b32 v176, v32, v45, v47 bitop3:0xde
	v_mov_b32_e32 v48, 0
	v_mov_b32_e32 v49, v170
	v_mov_b32_e32 v50, v170
	s_waitcnt lgkmcnt(0)
	v_mfma_f32_32x32x16_bf16 v[64:79], v[36:39], v[142:145], v[16:31]
	s_nop 6
	ds_read_b128 v[16:19], v175 offset:32768
	ds_read_b128 v[20:23], v175 offset:36864
	v_lshl_add_u64 v[24:25], s[78:79], 0, v[160:161]
	v_lshl_add_u64 v[28:29], s[78:79], 0, v[162:163]
	v_and_b32_e32 v36, 63, v42
	v_mov_b32_e32 v37, v170
	v_mov_b32_e32 v38, v170
	v_mov_b32_e32 v39, v170
	s_waitcnt lgkmcnt(1)
	v_mfma_f32_32x32x16_bf16 v[0:15], v[16:19], v[138:141], v[0:15]
	v_or_b32_e32 v16, 64, v46
	v_bitop3_b32 v173, v16, v45, v47 bitop3:0xde
	v_mov_b32_e32 v45, v170
	v_mov_b32_e32 v46, v170
	v_mov_b32_e32 v47, v170
	v_mov_b32_e32 v51, v170
	v_mov_b32_e32 v52, v170
	s_waitcnt lgkmcnt(0)
	v_mfma_f32_32x32x16_bf16 v[64:79], v[20:23], v[138:141], v[64:79]
	ds_read_b128 v[16:19], v173 offset:32768
	ds_read_b128 v[20:23], v173 offset:36864
	v_mov_b32_e32 v53, v170
	v_mov_b32_e32 v54, v170
	v_mov_b32_e32 v55, v170
	v_mov_b32_e32 v56, v170
	v_mov_b32_e32 v57, v170
	v_mov_b32_e32 v58, v170
	s_waitcnt lgkmcnt(1)
	v_mfma_f32_32x32x16_bf16 v[0:15], v[16:19], v[134:137], v[0:15]
	v_add_co_u32_e32 v16, vcc, s3, v40
	s_mov_b32 s3, 3
	s_nop 0
	v_addc_co_u32_e32 v17, vcc, 0, v41, vcc
	global_load_dwordx4 v[16:19], v[16:17], off offset:1152
	s_nop 0
	global_load_dwordx4 v[24:27], v[24:25], off
	ds_read_b128 v[32:35], v176 offset:36864
	global_load_dwordx4 v[28:31], v[28:29], off
	s_waitcnt lgkmcnt(1)
	v_mfma_f32_32x32x16_bf16 v[64:79], v[20:23], v[134:137], v[64:79]
	ds_read_b128 v[20:23], v176 offset:32768
	s_waitcnt vmcnt(0)
	s_waitcnt vmcnt(2)
	ds_write_b128 v179, v[16:19] offset:40960
	s_waitcnt vmcnt(1)
	ds_write_b128 v177, v[24:27] offset:16384
	s_waitcnt vmcnt(0)
	ds_write_b128 v178, v[28:31] offset:16384
	s_waitcnt lgkmcnt(3)
	v_mfma_f32_32x32x16_bf16 v[0:15], v[20:23], v[130:133], v[0:15]
	v_lshlrev_b32_e32 v20, 3, v36
	v_and_b32_e32 v21, 0xc0, v44
	v_lshlrev_b32_e32 v22, 1, v42
	v_and_or_b32 v21, v20, 24, v21
	v_and_b32_e32 v22, 32, v22
	v_and_b32_e32 v20, 0x100, v20
	v_or3_b32 v172, v21, v22, v20
	v_mfma_f32_32x32x16_bf16 v[64:79], v[32:35], v[130:133], v[64:79]
	s_nop 3
	v_exp_f32_e32 v165, v0
	v_exp_f32_e32 v167, v1
	v_exp_f32_e32 v157, v2
	v_exp_f32_e32 v166, v3
	v_exp_f32_e32 v155, v4
	v_exp_f32_e32 v164, v5
	v_exp_f32_e32 v154, v6
	v_exp_f32_e32 v156, v7
	v_exp_f32_e32 v151, v8
	v_exp_f32_e32 v153, v9
	v_exp_f32_e32 v149, v10
	v_exp_f32_e32 v152, v11
	v_exp_f32_e32 v147, v12
	v_exp_f32_e32 v150, v13
	v_exp_f32_e32 v146, v14
	v_exp_f32_e32 v148, v15
	v_or_b32_e32 v128, 0x4000, v172
	v_mov_b32_e32 v0, 0
	v_mov_b32_e32 v1, v170
	v_mov_b32_e32 v2, v170
	v_mov_b32_e32 v3, v170
	v_mov_b32_e32 v4, v170
	v_mov_b32_e32 v5, v170
	v_mov_b32_e32 v6, v170
	v_mov_b32_e32 v7, v170
	v_mov_b32_e32 v8, v170
	v_mov_b32_e32 v9, v170
	v_mov_b32_e32 v10, v170
	v_mov_b32_e32 v11, v170
	v_mov_b32_e32 v12, v170
	v_mov_b32_e32 v13, v170
	v_mov_b32_e32 v14, v170
	v_mov_b32_e32 v15, v170
	v_mov_b32_e32 v16, 0
	v_mov_b32_e32 v17, v170
	v_mov_b32_e32 v18, v170
	v_mov_b32_e32 v19, v170
	v_mov_b32_e32 v20, v170
	v_mov_b32_e32 v21, v170
	v_mov_b32_e32 v22, v170
	v_mov_b32_e32 v23, v170
	v_mov_b32_e32 v24, v170
	v_mov_b32_e32 v25, v170
	v_mov_b32_e32 v26, v170
	v_mov_b32_e32 v27, v170
	v_mov_b32_e32 v28, v170
	v_mov_b32_e32 v29, v170
	v_mov_b32_e32 v30, v170
	v_mov_b32_e32 v31, v170
	v_mov_b32_e32 v32, 0
	v_mov_b32_e32 v33, v170
	v_mov_b32_e32 v34, v170
	v_mov_b32_e32 v35, v170
	v_mov_b32_e32 v36, v170
	v_mov_b32_e32 v40, v170
	v_mov_b32_e32 v41, v170
	v_mov_b32_e32 v42, v170
	v_mov_b32_e32 v44, v170
	v_mov_b32_e32 v59, v170
	v_mov_b32_e32 v60, v170
	v_mov_b32_e32 v61, v170
	v_mov_b32_e32 v62, v170
	v_mov_b32_e32 v63, v170
	v_mov_b64_e32 v[238:239], s[4:5]
	v_mov_b64_e32 v[240:241], s[6:7]
	v_mov_b64_e32 v[242:243], s[8:9]
	v_mov_b64_e32 v[244:245], s[10:11]
	v_mov_b64_e32 v[246:247], s[12:13]
	v_mov_b64_e32 v[248:249], s[14:15]
	v_mov_b64_e32 v[250:251], s[16:17]
	v_mov_b64_e32 v[252:253], s[18:19]
	s_waitcnt lgkmcnt(0)
	s_barrier
; __device__ __forceinline__ void finishSM(f32x16& p0, f32x16& p1, float& l_reg, bf16x8& pa0, bf16x8& pa1, bf16x8& pa2, bf16x8& pa3) {
; #pragma unroll
;   for (int r = 0; r < 16; ++r) p1[r] = __builtin_amdgcn_exp2f(p1[r]);
;   float ps = 0;
; #pragma unroll
;   for (int r = 0; r < 16; ++r) ps += p0[r];
; #pragma unroll
;   for (int r = 0; r < 16; ++r) ps += p1[r];
;   { auto rr = __builtin_amdgcn_permlane32_swap(__float_as_uint(ps), __float_as_uint(ps), false, false);
;     ps = __uint_as_float(rr[0]) + __uint_as_float(rr[1]); }
;   l_reg += ps;
;     ...
;   PK4(p0, 0, pa0); PK4(p0, 8, pa1); PK4(p1, 0, pa2); PK4(p1, 8, pa3);
;     ...
; }
; template <int DQK, int QL>
; __device__ __forceinline__ void qkt(f32x16& p0, f32x16& p1, const char* Ks, const bf16x8 (&qr)[DQK / 16 - QL], const char* qlds, const int (&kofs)[4], float negM) {
;   constexpr int QR = DQK / 16 - QL;
; #pragma unroll
;   for (int r = 0; r < 16; ++r) { p0[r] = negM; p1[r] = negM; }
; #pragma unroll
;   for (int d0 = 0; d0 < DQK / 16; ++d0) {
;     const char* kp = Ks + kofs[d0 & 3] + (d0 >> 2) * 128;
;     bf16x8 b0 = *reinterpret_cast<const bf16x8*>(kp);
;     bf16x8 b1 = *reinterpret_cast<const bf16x8*>(kp + 32 * DQK * 2);
;     bf16x8 qf;
;     if constexpr (QL > 0) { if (d0 < QR) qf = qr[d0 < QR ? d0 : 0]; else qf = *reinterpret_cast<const bf16x8*>(qlds + (d0 - QR) * 1024); }
;     else qf = qr[d0];
;     p0 = __builtin_amdgcn_mfma_f32_32x32x16_bf16(b0, qf, p0, 0, 0, 0);
;     p1 = __builtin_amdgcn_mfma_f32_32x32x16_bf16(b1, qf, p1, 0, 0, 0);
;   }
; }
; template <int NCB> __device__ __forceinline__ int v_st(int k, int c) {
;   const int kk = (k & ~0xC) | ((k & 4) << 1) | ((k & 8) >> 1);
;   return ((kk >> 3) * NCB + (c >> 5)) * 512 + ((kk & 7) * 32 + (c & 31)) * 2;
; }
; __device__ __forceinline__ int v_rd_base(int lane) { return ((lane & 3) << 3) | (((lane >> 2) & 3) << 6) | (((lane >> 4) & 1) << 5) | (((lane >> 5) & 1) << 8); }
;     ...
;   for (; j + 1 < NT; j += 2) {
;     SBAR();
;     if constexpr (ONEP) { finishSM(pA0, pA1, l_reg, pa0, pa1, pa2, pa3); SBAR(); QKT(pB0, pB1, 1); }
;     else { QKT(pB0, pB1, 1); finishSM(pA0, pA1, l_reg, pa0, pa1, pa2, pa3); }
;     SBAR();
;     SLOAD(TKEY(j + 1), 0); SBAR();
;     pv_all<NCB>(o, vb0, pa0, pa1, pa2, pa3);
;     kb = TKEY(j);
;     partialSM<GM>(pB0, pB1, NEEDMASK(kb), kb, L, qpos, hi);
;     __syncthreads(); WAIT_V0(); SWRITE(0);
.LBB0_342:
	ds_read_b128 v[96:99], v174 offset:40960
	ds_read_b128 v[182:185], v174 offset:45056
	v_exp_f32_e32 v100, v68
	v_exp_f32_e32 v101, v69
	s_waitcnt lgkmcnt(1)
	v_mfma_f32_32x32x16_bf16 v[80:95], v[96:99], v[142:145], v[238:253]
	ds_read_b128 v[96:99], v175 offset:40960
	ds_read_b128 v[186:189], v175 offset:45056
	v_exp_f32_e32 v102, v70
	v_exp_f32_e32 v103, v71
	v_exp_f32_e32 v104, v72
	v_exp_f32_e32 v105, v73
	v_exp_f32_e32 v106, v74
	v_exp_f32_e32 v107, v75
	s_waitcnt lgkmcnt(1)
	v_mfma_f32_32x32x16_bf16 v[80:95], v[96:99], v[138:141], v[80:95]
	ds_read_b128 v[96:99], v173 offset:40960
	ds_read_b128 v[190:193], v173 offset:45056
	v_exp_f32_e32 v108, v76
	v_exp_f32_e32 v109, v77
	v_exp_f32_e32 v110, v78
	v_exp_f32_e32 v79, v79
	s_waitcnt lgkmcnt(1)
	v_mfma_f32_32x32x16_bf16 v[80:95], v[96:99], v[134:137], v[80:95]
	ds_read_b128 v[96:99], v176 offset:40960
	ds_read_b128 v[194:197], v176 offset:45056
	s_waitcnt lgkmcnt(1)
	v_mfma_f32_32x32x16_bf16 v[80:95], v[96:99], v[130:133], v[80:95]
	v_exp_f32_e32 v96, v64
	v_add_f32_e32 v64, 0, v165
	v_add_f32_e32 v64, v167, v64
	v_add_f32_e32 v64, v157, v64
	v_add_f32_e32 v64, v166, v64
	v_add_f32_e32 v64, v155, v64
	v_add_f32_e32 v64, v164, v64
	v_add_f32_e32 v64, v154, v64
	v_add_f32_e32 v64, v156, v64
	v_add_f32_e32 v64, v151, v64
	v_add_f32_e32 v64, v153, v64
	v_add_f32_e32 v64, v149, v64
	v_add_f32_e32 v64, v152, v64
	v_add_f32_e32 v64, v147, v64
	v_exp_f32_e32 v97, v65
	v_add_f32_e32 v64, v150, v64
	v_exp_f32_e32 v98, v66
	v_add_f32_e32 v64, v146, v64
	v_exp_f32_e32 v99, v67
	v_add_f32_e32 v64, v148, v64
	v_add_f32_e32 v64, v96, v64
	v_add_f32_e32 v64, v97, v64
	v_add_f32_e32 v64, v98, v64
	v_add_f32_e32 v64, v99, v64
	v_add_f32_e32 v64, v100, v64
	v_add_f32_e32 v64, v101, v64
	v_add_f32_e32 v64, v102, v64
	v_add_f32_e32 v64, v103, v64
	v_add_f32_e32 v64, v104, v64
	v_add_f32_e32 v64, v105, v64
	v_add_f32_e32 v64, v106, v64
	v_add_f32_e32 v64, v107, v64
	v_add_f32_e32 v64, v108, v64
	v_add_f32_e32 v64, v109, v64
	v_add_f32_e32 v64, v110, v64
	v_add_f32_e32 v180, v79, v64
	v_mov_b32_e32 v181, v180
	s_nop 1
	v_permlane32_swap_b32_e32 v180, v181
	v_cvt_pk_bf16_f32 v64, v165, v167
	v_cvt_pk_bf16_f32 v65, v157, v166
	v_cvt_pk_bf16_f32 v66, v155, v164
	v_cvt_pk_bf16_f32 v67, v154, v156
	v_cvt_pk_bf16_f32 v68, v151, v153
	v_cvt_pk_bf16_f32 v69, v149, v152
	v_cvt_pk_bf16_f32 v70, v147, v150
	v_cvt_pk_bf16_f32 v71, v146, v148
	v_cvt_pk_bf16_f32 v72, v96, v97
	v_cvt_pk_bf16_f32 v73, v98, v99
	v_cvt_pk_bf16_f32 v74, v100, v101
	v_cvt_pk_bf16_f32 v75, v102, v103
	v_cvt_pk_bf16_f32 v76, v104, v105
	v_cvt_pk_bf16_f32 v77, v106, v107
	v_cvt_pk_bf16_f32 v78, v108, v109
	v_cvt_pk_bf16_f32 v79, v110, v79
	s_nop 0
	v_permlane32_swap_b32_e32 v64, v66
	v_permlane32_swap_b32_e32 v65, v67
	v_permlane32_swap_b32_e32 v68, v70
	v_permlane32_swap_b32_e32 v69, v71
	v_permlane32_swap_b32_e32 v72, v74
	v_permlane32_swap_b32_e32 v73, v75
	v_permlane32_swap_b32_e32 v76, v78
	v_permlane32_swap_b32_e32 v77, v79
	v_mfma_f32_32x32x16_bf16 v[96:111], v[182:185], v[142:145], v[238:253]
	v_mfma_f32_32x32x16_bf16 v[96:111], v[186:189], v[138:141], v[96:111]
	s_add_u32 s100, s0, 0x590c000
	s_addc_u32 s101, s1, 0
	global_load_dwordx4 v[146:149], v158, s[100:101] offset:1408
	global_load_dwordx4 v[150:153], v160, s[100:101] offset:2304
	v_mfma_f32_32x32x16_bf16 v[96:111], v[190:193], v[134:137], v[96:111]
	global_load_dwordx4 v[154:157], v162, s[100:101] offset:2304
	s_waitcnt lgkmcnt(0)
	v_mfma_f32_32x32x16_bf16 v[96:111], v[194:197], v[130:133], v[96:111]
	ds_read_b64_tr_b16 v[112:113], v172 offset:0
	ds_read_b64_tr_b16 v[114:115], v172 offset:0x800
	ds_read_b64_tr_b16 v[116:117], v172 offset:0x1000
	ds_read_b64_tr_b16 v[118:119], v172 offset:0x1800
	ds_read_b64_tr_b16 v[120:121], v172 offset:0x2000
	ds_read_b64_tr_b16 v[122:123], v172 offset:0x2800
	ds_read_b64_tr_b16 v[124:125], v172 offset:0x3000
	ds_read_b64_tr_b16 v[126:127], v172 offset:0x3800
	s_nop 0
	s_waitcnt lgkmcnt(6)
	v_mfma_f32_32x32x16_bf16 v[0:15], v[64:67], v[112:115], v[0:15]
	ds_read_b64_tr_b16 v[112:113], v172 offset:0x200
	ds_read_b64_tr_b16 v[114:115], v172 offset:0xa00
	s_waitcnt lgkmcnt(6)
	v_mfma_f32_32x32x16_bf16 v[0:15], v[68:71], v[116:119], v[0:15]
	ds_read_b64_tr_b16 v[116:117], v172 offset:0x1200
	ds_read_b64_tr_b16 v[118:119], v172 offset:0x1a00
	s_waitcnt lgkmcnt(6)
	v_mfma_f32_32x32x16_bf16 v[0:15], v[72:75], v[120:123], v[0:15]
	ds_read_b64_tr_b16 v[120:121], v172 offset:0x2200
	ds_read_b64_tr_b16 v[122:123], v172 offset:0x2a00
	s_waitcnt lgkmcnt(6)
	v_mfma_f32_32x32x16_bf16 v[0:15], v[76:79], v[124:127], v[0:15]
	ds_read_b64_tr_b16 v[124:125], v172 offset:0x3200
	ds_read_b64_tr_b16 v[126:127], v172 offset:0x3a00
	s_waitcnt lgkmcnt(6)
	v_mfma_f32_32x32x16_bf16 v[16:31], v[64:67], v[112:115], v[16:31]
	ds_read_b64_tr_b16 v[112:113], v172 offset:0x400
	ds_read_b64_tr_b16 v[114:115], v172 offset:0xc00
	s_waitcnt lgkmcnt(6)
	v_mfma_f32_32x32x16_bf16 v[16:31], v[68:71], v[116:119], v[16:31]
	ds_read_b64_tr_b16 v[116:117], v172 offset:0x1400
	ds_read_b64_tr_b16 v[118:119], v172 offset:0x1c00
	s_waitcnt lgkmcnt(6)
	v_mfma_f32_32x32x16_bf16 v[16:31], v[72:75], v[120:123], v[16:31]
	ds_read_b64_tr_b16 v[120:121], v172 offset:0x2400
	ds_read_b64_tr_b16 v[122:123], v172 offset:0x2c00
	s_waitcnt lgkmcnt(6)
	v_mfma_f32_32x32x16_bf16 v[16:31], v[76:79], v[124:127], v[16:31]
	ds_read_b64_tr_b16 v[124:125], v172 offset:0x3400
	ds_read_b64_tr_b16 v[126:127], v172 offset:0x3c00
	s_waitcnt lgkmcnt(6)
	v_mfma_f32_32x32x16_bf16 v[32:47], v[64:67], v[112:115], v[32:47]
	ds_read_b64_tr_b16 v[112:113], v172 offset:0x600
	ds_read_b64_tr_b16 v[114:115], v172 offset:0xe00
	s_waitcnt lgkmcnt(6)
	v_mfma_f32_32x32x16_bf16 v[32:47], v[68:71], v[116:119], v[32:47]
	ds_read_b64_tr_b16 v[116:117], v172 offset:0x1600
	ds_read_b64_tr_b16 v[118:119], v172 offset:0x1e00
	s_waitcnt lgkmcnt(6)
	v_mfma_f32_32x32x16_bf16 v[32:47], v[72:75], v[120:123], v[32:47]
	ds_read_b64_tr_b16 v[120:121], v172 offset:0x2600
	ds_read_b64_tr_b16 v[122:123], v172 offset:0x2e00
	s_waitcnt lgkmcnt(6)
	v_mfma_f32_32x32x16_bf16 v[32:47], v[76:79], v[124:127], v[32:47]
	ds_read_b64_tr_b16 v[124:125], v172 offset:0x3600
	ds_read_b64_tr_b16 v[126:127], v172 offset:0x3e00
	s_waitcnt lgkmcnt(6)
	v_mfma_f32_32x32x16_bf16 v[48:63], v[64:67], v[112:115], v[48:63]
	s_add_i32 s20, s36, 64
	s_cmp_le_i32 s20, s59
	v_add_u32_e32 v182, s36, v171
	s_waitcnt lgkmcnt(4)
	v_mfma_f32_32x32x16_bf16 v[48:63], v[68:71], v[116:119], v[48:63]
	s_waitcnt lgkmcnt(2)
	v_mfma_f32_32x32x16_bf16 v[48:63], v[72:75], v[120:123], v[48:63]
	s_waitcnt lgkmcnt(0)
	v_mfma_f32_32x32x16_bf16 v[48:63], v[76:79], v[124:127], v[48:63]
	s_cbranch_scc1 .LBB0_344
; __device__ __forceinline__ int crow(int r, int hi) { return (r & 3) + 8 * (r >> 2) + 4 * hi; }
; template <bool GM>
; __device__ __forceinline__ void partialSM(f32x16& p0, f32x16& p1, bool mask, int kbase, int L, int qpos, int hi) {
;   if (mask) {
; #pragma unroll
;     for (int r = 0; r < 16; ++r) {
;       int k = kbase + crow(r, hi);
;       asm volatile("" : "+v"(k) : "v"(p0[r]));
;       bool ok = k < L;
;       if (GM) ok = ok && (k < 16 || abs(qpos - k) <= 128);
;       p0[r] = ok ? p0[r] : -1e30f;
;       int k2 = k + 32;
;       asm volatile("" : "+v"(k2) : "v"(p1[r]));
;       bool ok2 = k2 < L;
;       if (GM) ok2 = ok2 && (k2 < 16 || abs(qpos - k2) <= 128);
;       p1[r] = ok2 ? p1[r] : -1e30f;
;     }
	v_add_u32_e32 v64, 64, v182
	s_nop 0
	v_cmp_gt_i32_e32 vcc, s94, v64
	v_add_u32_e32 v64, 32, v64
	s_nop 0
	v_cndmask_b32_e32 v80, v233, v80, vcc
	v_cmp_gt_i32_e32 vcc, s94, v64
	v_add_u32_e32 v64, 0x41, v182
	s_nop 0
	v_cndmask_b32_e32 v96, v233, v96, vcc
	v_cmp_gt_i32_e32 vcc, s94, v64
	v_add_u32_e32 v64, 32, v64
	s_nop 0
	v_cndmask_b32_e32 v81, v233, v81, vcc
	v_cmp_gt_i32_e32 vcc, s94, v64
	v_add_u32_e32 v64, 0x42, v182
	s_nop 0
	v_cndmask_b32_e32 v97, v233, v97, vcc
	v_cmp_gt_i32_e32 vcc, s94, v64
	v_add_u32_e32 v64, 32, v64
	s_nop 0
	v_cndmask_b32_e32 v82, v233, v82, vcc
	v_cmp_gt_i32_e32 vcc, s94, v64
	v_add_u32_e32 v64, 0x43, v182
	s_nop 0
	v_cndmask_b32_e32 v98, v233, v98, vcc
	v_cmp_gt_i32_e32 vcc, s94, v64
	v_add_u32_e32 v64, 32, v64
	s_nop 0
	v_cndmask_b32_e32 v83, v233, v83, vcc
	v_cmp_gt_i32_e32 vcc, s94, v64
	v_add_u32_e32 v64, 0x48, v182
	s_nop 0
	v_cndmask_b32_e32 v99, v233, v99, vcc
	v_cmp_gt_i32_e32 vcc, s94, v64
	v_add_u32_e32 v64, 32, v64
	s_nop 0
	v_cndmask_b32_e32 v84, v233, v84, vcc
	v_cmp_gt_i32_e32 vcc, s94, v64
	v_add_u32_e32 v64, 0x49, v182
	s_nop 0
	v_cndmask_b32_e32 v100, v233, v100, vcc
	v_cmp_gt_i32_e32 vcc, s94, v64
	v_add_u32_e32 v64, 32, v64
	s_nop 0
	v_cndmask_b32_e32 v85, v233, v85, vcc
	v_cmp_gt_i32_e32 vcc, s94, v64
	v_add_u32_e32 v64, 0x4a, v182
	s_nop 0
	v_cndmask_b32_e32 v101, v233, v101, vcc
	v_cmp_gt_i32_e32 vcc, s94, v64
	v_add_u32_e32 v64, 32, v64
	s_nop 0
	v_cndmask_b32_e32 v86, v233, v86, vcc
	v_cmp_gt_i32_e32 vcc, s94, v64
	v_add_u32_e32 v64, 0x4b, v182
	s_nop 0
	v_cndmask_b32_e32 v102, v233, v102, vcc
	v_cmp_gt_i32_e32 vcc, s94, v64
	v_add_u32_e32 v64, 32, v64
	s_nop 0
	v_cndmask_b32_e32 v87, v233, v87, vcc
	v_cmp_gt_i32_e32 vcc, s94, v64
	v_add_u32_e32 v64, 0x50, v182
	s_nop 0
	v_cndmask_b32_e32 v103, v233, v103, vcc
	v_cmp_gt_i32_e32 vcc, s94, v64
	v_add_u32_e32 v64, 32, v64
	s_nop 0
	v_cndmask_b32_e32 v88, v233, v88, vcc
	v_cmp_gt_i32_e32 vcc, s94, v64
	v_add_u32_e32 v64, 0x51, v182
	s_nop 0
	v_cndmask_b32_e32 v104, v233, v104, vcc
	v_cmp_gt_i32_e32 vcc, s94, v64
	v_add_u32_e32 v64, 32, v64
	s_nop 0
	v_cndmask_b32_e32 v89, v233, v89, vcc
	v_cmp_gt_i32_e32 vcc, s94, v64
	v_add_u32_e32 v64, 0x52, v182
	s_nop 0
	v_cndmask_b32_e32 v105, v233, v105, vcc
	v_cmp_gt_i32_e32 vcc, s94, v64
	v_add_u32_e32 v64, 32, v64
	s_nop 0
	v_cndmask_b32_e32 v90, v233, v90, vcc
	v_cmp_gt_i32_e32 vcc, s94, v64
	v_add_u32_e32 v64, 0x53, v182
	s_nop 0
	v_cndmask_b32_e32 v106, v233, v106, vcc
	v_cmp_gt_i32_e32 vcc, s94, v64
	v_add_u32_e32 v64, 32, v64
	s_nop 0
	v_cndmask_b32_e32 v91, v233, v91, vcc
	v_cmp_gt_i32_e32 vcc, s94, v64
	v_add_u32_e32 v64, 0x58, v182
	s_nop 0
	v_cndmask_b32_e32 v107, v233, v107, vcc
	v_cmp_gt_i32_e32 vcc, s94, v64
	v_add_u32_e32 v64, 32, v64
	s_nop 0
	v_cndmask_b32_e32 v92, v233, v92, vcc
	v_cmp_gt_i32_e32 vcc, s94, v64
	v_add_u32_e32 v64, 0x59, v182
	s_nop 0
	v_cndmask_b32_e32 v108, v233, v108, vcc
	v_cmp_gt_i32_e32 vcc, s94, v64
	v_add_u32_e32 v64, 32, v64
	s_nop 0
	v_cndmask_b32_e32 v93, v233, v93, vcc
	v_cmp_gt_i32_e32 vcc, s94, v64
	v_add_u32_e32 v64, 0x5a, v182
	s_nop 0
	v_cndmask_b32_e32 v109, v233, v109, vcc
	v_cmp_gt_i32_e32 vcc, s94, v64
	v_add_u32_e32 v64, 32, v64
	s_nop 0
	v_cndmask_b32_e32 v94, v233, v94, vcc
	v_cmp_gt_i32_e32 vcc, s94, v64
	v_add_u32_e32 v64, 0x5b, v182
	s_nop 0
	v_cndmask_b32_e32 v110, v233, v110, vcc
	v_cmp_gt_i32_e32 vcc, s94, v64
	v_add_u32_e32 v64, 32, v64
	s_nop 0
	v_cndmask_b32_e32 v95, v233, v95, vcc
	v_cmp_gt_i32_e32 vcc, s94, v64
	s_nop 1
	v_cndmask_b32_e32 v111, v233, v111, vcc
; #define WAIT_V0() asm volatile("s_waitcnt vmcnt(0)" ::: "memory")
; #define SBAR() __builtin_amdgcn_sched_barrier(0)
; #define SWRITE(b) do { FRESH_COORDS(); \
;     if constexpr (!KDMA) { _Pragma("unroll") for (int i = 0; i < KC; ++i) *reinterpret_cast<bf16x8*>(shm + (b) * SHM_K + klo[i]) = ks[i]; } \
;     _Pragma("unroll") for (int i = 0; i < VC; ++i) *reinterpret_cast<bf16x8*>(shm + (b) * SHM_V + vlo[i]) = vs[i]; } while (0)
; #define QKT(P0, P1, BUF) qkt<DQK, QL>(P0, P1, shm + K_OFF + (BUF) * SHM_K, qr, qlds, kofs, negM)
;     ...
;     partialSM<GM>(pB0, pB1, NEEDMASK(kb), kb, L, qpos, hi);
;     __syncthreads(); WAIT_V0(); SWRITE(0);
;     __syncthreads();
;     SBAR();
;     if constexpr (ONEP) { finishSM(pB0, pB1, l_reg, pa0, pa1, pa2, pa3); SBAR(); QKT(pA0, pA1, 0); }
;     else { QKT(pA0, pA1, 0); finishSM(pB0, pB1, l_reg, pa0, pa1, pa2, pa3); }
;     SBAR();
;     if (j + 2 < NT) SLOAD(TKEY(j + 2), 1);
.LBB0_344:
	s_barrier
	s_waitcnt vmcnt(0)
	s_waitcnt vmcnt(2)
	ds_write_b128 v179, v[146:149] offset:32768
	s_waitcnt vmcnt(1)
	ds_write_b128 v177, v[150:153]
	s_waitcnt vmcnt(0)
	ds_write_b128 v178, v[154:157]
	v_exp_f32_e32 v183, v80
	v_exp_f32_e32 v188, v81
	v_exp_f32_e32 v189, v82
	v_exp_f32_e32 v190, v83
	v_exp_f32_e32 v191, v84
	v_exp_f32_e32 v192, v85
	v_exp_f32_e32 v193, v86
	v_exp_f32_e32 v194, v87
	v_exp_f32_e32 v195, v88
	v_exp_f32_e32 v196, v89
	v_exp_f32_e32 v197, v90
	v_exp_f32_e32 v198, v91
	v_exp_f32_e32 v199, v92
	v_exp_f32_e32 v200, v93
	v_exp_f32_e32 v201, v94
	v_exp_f32_e32 v202, v95
	s_waitcnt lgkmcnt(0)
	s_barrier
	ds_read_b128 v[64:67], v174 offset:32768
	ds_read_b128 v[184:187], v174 offset:36864
	v_exp_f32_e32 v111, v111
	s_waitcnt lgkmcnt(1)
	v_mfma_f32_32x32x16_bf16 v[80:95], v[64:67], v[142:145], v[238:253]
	s_waitcnt lgkmcnt(0)
	v_mfma_f32_32x32x16_bf16 v[64:79], v[184:187], v[142:145], v[238:253]
	ds_read_b128 v[112:115], v175 offset:32768
	ds_read_b128 v[116:119], v175 offset:36864
	v_exp_f32_e32 v120, v102
	v_exp_f32_e32 v121, v103
	v_exp_f32_e32 v122, v104
	v_exp_f32_e32 v123, v105
	v_exp_f32_e32 v124, v106
	v_exp_f32_e32 v125, v107
	s_waitcnt lgkmcnt(1)
	v_mfma_f32_32x32x16_bf16 v[80:95], v[112:115], v[138:141], v[80:95]
	v_exp_f32_e32 v126, v108
	v_exp_f32_e32 v127, v109
	v_exp_f32_e32 v184, v110
	s_waitcnt lgkmcnt(0)
	v_mfma_f32_32x32x16_bf16 v[64:79], v[116:119], v[138:141], v[64:79]
	ds_read_b128 v[112:115], v173 offset:32768
	ds_read_b128 v[116:119], v173 offset:36864
	s_waitcnt lgkmcnt(1)
	v_mfma_f32_32x32x16_bf16 v[80:95], v[112:115], v[134:137], v[80:95]
	s_waitcnt lgkmcnt(0)
	v_mfma_f32_32x32x16_bf16 v[64:79], v[116:119], v[134:137], v[64:79]
	ds_read_b128 v[112:115], v176 offset:32768
	ds_read_b128 v[116:119], v176 offset:36864
	s_waitcnt lgkmcnt(1)
	v_mfma_f32_32x32x16_bf16 v[80:95], v[112:115], v[130:133], v[80:95]
	v_exp_f32_e32 v114, v96
	v_add_f32_e32 v96, 0, v183
	v_add_f32_e32 v96, v188, v96
	v_add_f32_e32 v96, v189, v96
	v_add_f32_e32 v96, v190, v96
	v_add_f32_e32 v96, v191, v96
	v_add_f32_e32 v96, v192, v96
	v_add_f32_e32 v96, v193, v96
	v_add_f32_e32 v96, v194, v96
	v_add_f32_e32 v96, v195, v96
	v_add_f32_e32 v96, v196, v96
	v_add_f32_e32 v96, v197, v96
	v_add_f32_e32 v96, v198, v96
	v_add_f32_e32 v96, v199, v96
	v_exp_f32_e32 v115, v97
	v_add_f32_e32 v96, v200, v96
	s_waitcnt lgkmcnt(0)
	v_mfma_f32_32x32x16_bf16 v[64:79], v[116:119], v[130:133], v[64:79]
	v_exp_f32_e32 v116, v98
	v_add_f32_e32 v96, v201, v96
	v_exp_f32_e32 v117, v99
	v_add_f32_e32 v96, v202, v96
	v_exp_f32_e32 v118, v100
	v_add_f32_e32 v96, v114, v96
	v_exp_f32_e32 v119, v101
	v_add_f32_e32 v96, v115, v96
	v_add_f32_e32 v96, v116, v96
	v_add_f32_e32 v96, v117, v96
	v_add_f32_e32 v96, v118, v96
	v_add_f32_e32 v96, v119, v96
	v_add_f32_e32 v96, v120, v96
	v_add_f32_e32 v96, v121, v96
	v_add_f32_e32 v96, v122, v96
	v_add_f32_e32 v96, v123, v96
	v_add_f32_e32 v96, v124, v96
	v_add_f32_e32 v96, v125, v96
	v_add_f32_e32 v96, v126, v96
	v_add_f32_e32 v96, v127, v96
	v_add_f32_e32 v96, v184, v96
	v_add_f32_e32 v112, v111, v96
	v_mov_b32_e32 v113, v112
	v_cvt_pk_bf16_f32 v96, v183, v188
	v_cvt_pk_bf16_f32 v97, v189, v190
	v_cvt_pk_bf16_f32 v98, v191, v192
	v_cvt_pk_bf16_f32 v99, v193, v194
	v_cvt_pk_bf16_f32 v100, v195, v196
	v_cvt_pk_bf16_f32 v101, v197, v198
	v_cvt_pk_bf16_f32 v102, v199, v200
	v_cvt_pk_bf16_f32 v103, v201, v202
	v_cvt_pk_bf16_f32 v104, v114, v115
	v_cvt_pk_bf16_f32 v105, v116, v117
	v_cvt_pk_bf16_f32 v106, v118, v119
	v_cvt_pk_bf16_f32 v107, v120, v121
	v_cvt_pk_bf16_f32 v108, v122, v123
	v_cvt_pk_bf16_f32 v109, v124, v125
	v_cvt_pk_bf16_f32 v110, v126, v127
	v_cvt_pk_bf16_f32 v111, v184, v111
	s_nop 1
	v_permlane32_swap_b32_e32 v112, v113
	v_permlane32_swap_b32_e32 v96, v98
	v_permlane32_swap_b32_e32 v97, v99
	v_permlane32_swap_b32_e32 v100, v102
	v_permlane32_swap_b32_e32 v101, v103
	v_permlane32_swap_b32_e32 v104, v106
	v_permlane32_swap_b32_e32 v105, v107
	v_permlane32_swap_b32_e32 v108, v110
	v_permlane32_swap_b32_e32 v109, v111
	s_cmp_lt_u32 s3, s58
	s_cselect_b64 s[22:23], -1, 0
	s_cmp_ge_u32 s3, s58
	s_cselect_b64 s[20:21], -1, 0
	s_and_b64 vcc, exec, s[20:21]
	s_cbranch_vccnz .LBB0_346
	s_add_u32 s100, s0, 0x593c000
	s_addc_u32 s101, s1, 0
	global_load_dwordx4 v[146:149], v158, s[100:101] offset:1408
	global_load_dwordx4 v[150:153], v160, s[100:101] offset:2304
	global_load_dwordx4 v[154:157], v162, s[100:101] offset:2304

; #define WAIT_V0() asm volatile("s_waitcnt vmcnt(0)" ::: "memory")
; __device__ __forceinline__ int v_rd_base(int lane) { return ((lane & 3) << 3) | (((lane >> 2) & 3) << 6) | (((lane >> 4) & 1) << 5) | (((lane >> 5) & 1) << 8); }
; #define V_COORDS(T) do { if constexpr (VC == 2) { const int sr = (T) >> 4, sc = ((T) & 15) * 8; vgo[0] = sr * LDV + sc; vgo[VC - 1] = (32 + sr) * LDV + sc; vlo[0] = v_st<NCB>(sr, sc); vlo[VC - 1] = v_st<NCB>(32 + sr, sc); } \
;     else { const int sr = (T) >> 3, sc = ((T) & 7) * 8; vgo[0] = sr * LDV + sc; vlo[0] = v_st<NCB>(sr, sc); } } while (0)
; #define SWRITE(b) do { FRESH_COORDS(); \
;     if constexpr (!KDMA) { _Pragma("unroll") for (int i = 0; i < KC; ++i) *reinterpret_cast<bf16x8*>(shm + (b) * SHM_K + klo[i]) = ks[i]; } \
;     _Pragma("unroll") for (int i = 0; i < VC; ++i) *reinterpret_cast<bf16x8*>(shm + (b) * SHM_V + vlo[i]) = vs[i]; } while (0)
;   const int tidx = ltid(p.wv);
;   constexpr int NCB = DV / 32, KC = DQK / 64, VC = DV / 64, KRS = DQK * 2, CPR = DQK / 8;
;   constexpr int SHM_V = 64 * DV * 2, SHM_K = 64 * DQK * 2, K_OFF = 32768;
;   const int tid = tidx, wid = tid >> 6, lane = tid & 63, r32 = lane & 31, hi = lane >> 5;
;   constexpr int QR = DQK / 16 - QL;
;   bf16x8 qr[QR];
;   char* qlds = shm + 81920 + wid * (QL * 1024) + lane * 16;
; #pragma unroll
;   for (int d0 = 0; d0 < QR; ++d0) qr[d0] = *reinterpret_cast<const bf16x8*>(qlane + d0 * 16);
;   constexpr bool KDMA = DQK > 128;
;   int kgo[KC], klo[KC], vgo[VC], vlo[VC];
;     ...
;   if constexpr (KDMA) {
;   } else {
; #pragma unroll
;     for (int i = 0; i < KC; ++i) { const int c = tid + i * 512, row = c / CPR, cc = c % CPR; kgo[i] = row * LDK + cc * 8; klo[i] = K_OFF + KSWZ(KRS, row, cc * 16); }
;     V_COORDS(tid);
;   }
;   const int vb0 = (int)(uintptr_t)shm + v_rd_base(lane);
;   int kofs[4];
; #pragma unroll
;   for (int b = 0; b < 4; ++b) kofs[b] = (r32 ^ ((r32 >> 3) & 1)) * KRS + ((b * 32 + hi * 16) ^ ((r32 & 7) << 4));
;   bf16x8 ks[KC], vs[VC];
;     ...
;   f32x16 pA0, pA1, pB0, pB1; bf16x8 pa0, pa1, pa2, pa3;
;   __syncthreads();
;   if constexpr (QL > 0) {
; #pragma unroll
;     for (int d0 = 0; d0 < QL; ++d0) *reinterpret_cast<bf16x8*>(qlds + d0 * 1024) = *reinterpret_cast<const bf16x8*>(qlane + (QR + d0) * 16);
;   }
;   int kb = TKEY(0);
;   SLOAD(kb, 0); WAIT_V0(); SWRITE(0); __syncthreads();
.LBB0_368:
	global_load_dword v38, v129, s[70:71]
	v_mbcnt_lo_u32_b32 v2, -1, 0
	v_mbcnt_hi_u32_b32 v2, -1, v2
	s_mul_i32 s6, s7, s94
	v_or_b32_e32 v0, s79, v2
	s_lshl_b32 s81, s3, 8
	v_ashrrev_i32_e32 v0, 1, v0
	v_and_b32_e32 v1, 31, v2
	s_add_i32 s81, s81, s6
	v_and_b32_e32 v0, 0xffffffe0, v0
	v_add3_u32 v3, v1, s81, v0
	v_mov_b64_e32 v[0:1], s[68:69]
	s_mul_i32 s26, s20, 0xc0
	v_mad_i64_i32 v[0:1], s[4:5], v3, s86, v[0:1]
	s_lshl_b64 s[8:9], s[26:27], 1
	v_lshrrev_b32_e32 v2, 1, v2
	v_lshl_add_u64 v[0:1], v[0:1], 0, s[8:9]
	v_and_b32_e32 v128, 16, v2
	v_lshl_add_u64 v[32:33], v[0:1], 0, v[128:129]
	v_mbcnt_lo_u32_b32 v62, -1, 0
	v_mbcnt_hi_u32_b32 v62, -1, v62
	global_load_dwordx4 v[138:141], v[32:33], off
	global_load_dwordx4 v[134:137], v[32:33], off offset:32
	global_load_dwordx4 v[130:133], v[32:33], off offset:64
	s_waitcnt vmcnt(63) expcnt(7) lgkmcnt(15)
	s_barrier
	global_load_dwordx4 v[0:3], v[32:33], off offset:96
	global_load_dwordx4 v[4:7], v[32:33], off offset:128
	global_load_dwordx4 v[8:11], v[32:33], off offset:160
	global_load_dwordx4 v[12:15], v[32:33], off offset:192
	global_load_dwordx4 v[16:19], v[32:33], off offset:224
	global_load_dwordx4 v[20:23], v[32:33], off offset:256
	global_load_dwordx4 v[24:27], v[32:33], off offset:288
	global_load_dwordx4 v[28:31], v[32:33], off offset:320
	global_load_dwordx4 v[34:37], v[32:33], off offset:352
	v_or_b32_e32 v161, s79, v62
	v_ashrrev_i32_e32 v42, 6, v161
	s_movk_i32 s3, 0x2400
	v_mul_lo_u32 v43, v42, s3
	s_ashr_i32 s7, s6, 31
	s_mul_i32 s83, s6, 0x600
	s_mul_hi_i32 s55, s6, 0x600
	v_and_b32_e32 v33, 63, v62
	v_and_b32_e32 v39, 31, v62
	v_lshrrev_b32_e32 v40, 3, v62
	v_lshlrev_b32_e32 v162, 4, v33
	v_add_u32_e32 v163, 0x14000, v43
	v_bitop3_b32 v39, v40, v39, 1 bitop3:0x6c
	v_mov_b32_e32 v40, v161
	v_or_b32_e32 v80, v163, v162
	v_lshlrev_b32_e32 v63, 10, v42
	v_add_u32_e32 v164, 0x8000, v63
	v_add_u32_e32 v165, 0xa000, v63
	v_add_u32_e32 v166, 0xc000, v63
	v_lshlrev_b32_e32 v41, 4, v62
	v_and_b32_e32 v47, 0x70, v41
	v_mov_b32_e32 v41, v161
	v_bfe_u32 v32, v62, 5, 1
	v_lshlrev_b32_e32 v46, 4, v32
	v_mul_u32_u24_e32 v48, 0x180, v39
	v_bitop3_b32 v152, v46, v48, v47 bitop3:0xde
	v_add_u32_e32 v168, 0xe000, v63
	v_mov_b32_e32 v150, 0
	v_readfirstlane_b32 s21, v168
	v_lshlrev_b32_e32 v154, 2, v32
	v_add_u32_e32 v160, 0xe000, v152
	s_mov_b32 s87, 0
	v_mov_b32_e32 v32, 0
	s_waitcnt vmcnt(8)
	ds_write_b128 v80, v[0:3]
	s_waitcnt vmcnt(7)
	ds_write_b128 v80, v[4:7] offset:1024
	s_waitcnt vmcnt(6)
	ds_write_b128 v80, v[8:11] offset:2048
	s_waitcnt vmcnt(5)
	ds_write_b128 v80, v[12:15] offset:3072
	s_waitcnt vmcnt(4)
	ds_write_b128 v80, v[16:19] offset:4096
	s_waitcnt vmcnt(3)
	ds_write_b128 v80, v[20:23] offset:5120
	s_waitcnt vmcnt(2)
	ds_write_b128 v80, v[24:27] offset:6144
	s_waitcnt vmcnt(1)
	ds_write_b128 v80, v[28:31] offset:7168
	s_waitcnt vmcnt(0)
	ds_write_b128 v80, v[34:37] offset:8192
	v_readfirstlane_b32 s3, v38
	s_xor_b32 s4, s3, 0x80000000
	s_add_u32 s3, s65, s83
	s_addc_u32 s5, s76, s55
	s_add_u32 s74, s3, s8
	s_addc_u32 s75, s5, s9
	s_lshl_b64 s[22:23], s[6:7], 10
	s_add_u32 s3, s77, s22
	v_lshlrev_b32_e32 v0, 3, v40
	v_lshlrev_b32_e32 v1, 5, v40
	v_and_b32_e32 v0, 0x78, v0
	s_addc_u32 s5, s78, s23
	s_lshl_b32 s26, s20, 7
	s_lshl_b32 s6, s20, 8
	v_and_or_b32 v0, v1, s24, v0
	s_add_u32 s72, s3, s6
	v_add_u32_e32 v2, 0x4000, v0
	s_addc_u32 s73, s5, 0
	v_ashrrev_i32_e32 v1, 31, v0
	v_ashrrev_i32_e32 v3, 31, v2
	v_lshl_add_u64 v[0:1], v[0:1], 1, s[72:73]
	v_lshl_add_u64 v[4:5], v[2:3], 1, s[72:73]
	global_load_dwordx4 v[0:3], v[0:1], off
	s_nop 0
	global_load_dwordx4 v[4:7], v[4:5], off
	v_mul_hi_i32 v8, v40, s82
	v_add_u32_e32 v9, 0x200, v40
	v_add_u32_e32 v10, 0x400, v40
	v_lshrrev_b32_e32 v11, 31, v8
	v_ashrrev_i32_e32 v8, 2, v8
	v_mul_hi_i32 v12, v9, s82
	v_mul_hi_i32 v13, v10, s82
	v_add_u32_e32 v8, v8, v11
	v_lshrrev_b32_e32 v11, 31, v12
	v_ashrrev_i32_e32 v12, 2, v12
	v_lshrrev_b32_e32 v14, 31, v13
	v_ashrrev_i32_e32 v13, 2, v13
	v_mul_lo_u32 v15, v8, 24
	v_lshrrev_b32_e32 v16, 3, v8
	v_add_u32_e32 v11, v12, v11
	v_add_u32_e32 v12, v13, v14
	v_sub_u32_e32 v13, v40, v15
	v_bitop3_b32 v8, v16, v8, 1 bitop3:0x6c
	v_mul_lo_u32 v14, v11, 24
	v_lshrrev_b32_e32 v15, 3, v11
	v_mul_lo_u32 v16, v12, 24
	v_lshrrev_b32_e32 v17, 3, v12
	v_bitop3_b32 v13, v8, v13, 7 bitop3:0x6c
	v_mul_lo_u32 v8, v8, s85
	v_sub_u32_e32 v9, v9, v14
	v_bitop3_b32 v11, v15, v11, 1 bitop3:0x6c
	v_sub_u32_e32 v10, v10, v16
	v_bitop3_b32 v12, v17, v12, 1 bitop3:0x6c
	v_lshl_add_u32 v8, v13, 3, v8
	v_bitop3_b32 v9, v11, v9, 7 bitop3:0x6c
	v_mul_lo_u32 v11, v11, s85
	v_readfirstlane_b32 s3, v164
	v_bitop3_b32 v13, v12, v10, 7 bitop3:0x6c
	v_mul_lo_u32 v12, v12, s85
	v_lshl_add_u32 v10, v9, 3, v11
	v_ashrrev_i32_e32 v9, 31, v8
	v_readfirstlane_b32 s5, v165
	v_lshl_add_u32 v12, v13, 3, v12
	v_lshl_add_u64 v[8:9], v[8:9], 1, s[74:75]
	v_ashrrev_i32_e32 v11, 31, v10
	s_mov_b32 m0, s3
	v_readfirstlane_b32 s6, v166
	v_ashrrev_i32_e32 v13, 31, v12
	global_load_lds_dwordx4 v[8:9], off
	v_lshl_add_u64 v[8:9], v[10:11], 1, s[74:75]
	s_mov_b32 m0, s5
	v_lshl_add_u64 v[10:11], v[12:13], 1, s[74:75]
	global_load_lds_dwordx4 v[8:9], off
	s_mov_b32 m0, s6
	s_mov_b32 s18, s4
	global_load_lds_dwordx4 v[10:11], off
	s_waitcnt vmcnt(0)
	s_mov_b32 s19, s4
	v_ashrrev_i32_e32 v8, 4, v41
	v_add_u32_e32 v11, 32, v8
	v_and_b32_e32 v12, 0xfffff0, v8
	v_lshlrev_b32_e32 v13, 1, v8
	v_and_or_b32 v12, v13, 8, v12
	v_and_b32_e32 v13, 0xfffff0, v11
	v_lshlrev_b32_e32 v11, 1, v11
	v_bfe_u32 v9, v41, 2, 2
	v_lshrrev_b32_e32 v14, 1, v8
	v_and_b32_e32 v8, 3, v8
	v_lshrrev_b32_e32 v12, 1, v12
	v_and_or_b32 v11, v11, 8, v13
	v_lshlrev_b32_e32 v10, 4, v41
	v_and_or_b32 v8, v14, 4, v8
	v_or_b32_e32 v12, v12, v9
	v_lshrrev_b32_e32 v11, 1, v11
	v_and_b32_e32 v10, 48, v10
	v_lshlrev_b32_e32 v8, 6, v8
	v_lshlrev_b32_e32 v12, 9, v12
	v_or_b32_e32 v9, v11, v9
	v_lshlrev_b32_e32 v9, 9, v9
	v_or3_b32 v11, v12, v8, v10
	v_or3_b32 v8, v9, v8, v10
	s_waitcnt vmcnt(0)
	ds_write_b128 v11, v[0:3]
	ds_write_b128 v8, v[4:7]
	s_waitcnt lgkmcnt(0)
	s_barrier
; #define WAIT_V0() asm volatile("s_waitcnt vmcnt(0)" ::: "memory")
; #define SWRITE(b) do { FRESH_COORDS(); \
;     if constexpr (!KDMA) { _Pragma("unroll") for (int i = 0; i < KC; ++i) *reinterpret_cast<bf16x8*>(shm + (b) * SHM_K + klo[i]) = ks[i]; } \
;     _Pragma("unroll") for (int i = 0; i < VC; ++i) *reinterpret_cast<bf16x8*>(shm + (b) * SHM_V + vlo[i]) = vs[i]; } while (0)
; #define QKT(P0, P1, BUF) qkt<DQK, QL>(P0, P1, shm + K_OFF + (BUF) * SHM_K, qr, qlds, kofs, negM)
; template <int DQK, int QL>
; __device__ __forceinline__ void qkt(f32x16& p0, f32x16& p1, const char* Ks, const bf16x8 (&qr)[DQK / 16 - QL], const char* qlds, const int (&kofs)[4], float negM) {
;   constexpr int QR = DQK / 16 - QL;
; #pragma unroll
;   for (int r = 0; r < 16; ++r) { p0[r] = negM; p1[r] = negM; }
; #pragma unroll
;   for (int d0 = 0; d0 < DQK / 16; ++d0) {
;     const char* kp = Ks + kofs[d0 & 3] + (d0 >> 2) * 128;
;     bf16x8 b0 = *reinterpret_cast<const bf16x8*>(kp);
;     bf16x8 b1 = *reinterpret_cast<const bf16x8*>(kp + 32 * DQK * 2);
;     bf16x8 qf;
;     if constexpr (QL > 0) { if (d0 < QR) qf = qr[d0 < QR ? d0 : 0]; else qf = *reinterpret_cast<const bf16x8*>(qlds + (d0 - QR) * 1024); }
;     else qf = qr[d0];
;     p0 = __builtin_amdgcn_mfma_f32_32x32x16_bf16(b0, qf, p0, 0, 0, 0);
;     p1 = __builtin_amdgcn_mfma_f32_32x32x16_bf16(b1, qf, p1, 0, 0, 0);
;   }
; }
;     ...
;   int kb = TKEY(0);
;   SLOAD(kb, 0); WAIT_V0(); SWRITE(0); __syncthreads();
;   QKT(pA0, pA1, 0);
;   partialSM<GM>(pA0, pA1, NEEDMASK(kb), kb, L, qpos, hi);
	ds_read_b128 v[34:37], v152 offset:32768
	ds_read_b128 v[38:41], v152 offset:32896
	s_mov_b32 s5, s4
	s_mov_b32 s6, s4
	s_mov_b32 s7, s4
	s_mov_b32 s8, s4
	s_mov_b32 s9, s4
	s_mov_b32 s10, s4
	s_mov_b32 s11, s4
	s_mov_b32 s12, s4
	s_mov_b32 s13, s4
	s_mov_b32 s14, s4
	s_mov_b32 s15, s4
	s_mov_b32 s16, s4
	s_mov_b32 s17, s4
	v_mov_b64_e32 v[30:31], s[18:19]
	v_mov_b64_e32 v[28:29], s[16:17]
	v_mov_b64_e32 v[26:27], s[14:15]
	v_mov_b64_e32 v[24:25], s[12:13]
	v_mov_b64_e32 v[22:23], s[10:11]
	v_mov_b64_e32 v[20:21], s[8:9]
	v_mov_b64_e32 v[18:19], s[6:7]
	v_mov_b64_e32 v[16:17], s[4:5]
	ds_read_b128 v[42:45], v152 offset:33024
	s_add_u32 s74, s74, 0x18000
	s_waitcnt lgkmcnt(2)
	v_mfma_f32_32x32x16_bf16 v[0:15], v[34:37], v[138:141], v[16:31]
	ds_read_b128 v[34:37], v152 offset:45056
	s_addc_u32 s75, s75, 0
	s_add_u32 s72, s72, 0x10000
	s_addc_u32 s73, s73, 0
	s_mov_b32 m0, s21
	s_nop 1
	v_or_b32_e32 v16, 32, v46
	v_bitop3_b32 v156, v16, v48, v47 bitop3:0xde
	v_mov_b64_e32 v[30:31], s[18:19]
	v_mov_b64_e32 v[28:29], s[16:17]
	v_mov_b64_e32 v[26:27], s[14:15]
	v_mov_b64_e32 v[24:25], s[12:13]
	v_mov_b64_e32 v[22:23], s[10:11]
	v_mov_b64_e32 v[20:21], s[8:9]
	v_mov_b64_e32 v[18:19], s[6:7]
	v_mov_b64_e32 v[16:17], s[4:5]
	s_mov_b32 s3, 3
	v_add_u32_e32 v159, 0xe000, v156
	s_waitcnt lgkmcnt(0)
	v_mfma_f32_32x32x16_bf16 v[64:79], v[34:37], v[138:141], v[16:31]
	s_nop 6
	ds_read_b128 v[16:19], v156 offset:32768
	ds_read_b128 v[20:23], v156 offset:32896
	v_or_b32_e32 v24, 64, v46
	v_bitop3_b32 v155, v24, v48, v47 bitop3:0xde
	ds_read_b128 v[24:27], v156 offset:33024
	v_or_b32_e32 v34, 0x60, v46
	v_bitop3_b32 v153, v34, v48, v47 bitop3:0xde
	v_add_u32_e32 v158, 0xe000, v155
	s_waitcnt lgkmcnt(2)
	v_mfma_f32_32x32x16_bf16 v[0:15], v[16:19], v[134:137], v[0:15]
	ds_read_b128 v[16:19], v156 offset:45056
	v_add_u32_e32 v157, 0xe000, v153
	s_waitcnt lgkmcnt(0)
	v_mfma_f32_32x32x16_bf16 v[64:79], v[16:19], v[134:137], v[64:79]
	ds_read_b128 v[16:19], v155 offset:32768
	ds_read_b128 v[28:31], v155 offset:32896
	ds_read_b128 v[34:37], v155 offset:33024
	s_waitcnt lgkmcnt(2)
	v_mfma_f32_32x32x16_bf16 v[0:15], v[16:19], v[130:133], v[0:15]
	ds_read_b128 v[16:19], v155 offset:45056
	s_waitcnt lgkmcnt(0)
	v_mfma_f32_32x32x16_bf16 v[64:79], v[16:19], v[130:133], v[64:79]
	ds_read_b128 v[16:19], v153 offset:32768
	ds_read_b128 v[46:49], v80
	ds_read_b128 v[50:53], v80 offset:1024
	ds_read_b128 v[54:57], v153 offset:32896
	s_waitcnt lgkmcnt(2)
	v_mfma_f32_32x32x16_bf16 v[0:15], v[16:19], v[46:49], v[0:15]
	ds_read_b128 v[16:19], v153 offset:45056
	ds_read_b128 v[58:61], v153 offset:33024
	s_waitcnt lgkmcnt(1)
	v_mfma_f32_32x32x16_bf16 v[64:79], v[16:19], v[46:49], v[64:79]
	v_mfma_f32_32x32x16_bf16 v[0:15], v[38:41], v[50:53], v[0:15]
	ds_read_b128 v[16:19], v152 offset:45184
	ds_read_b128 v[38:41], v152 offset:45312
	s_waitcnt lgkmcnt(1)
	v_mfma_f32_32x32x16_bf16 v[64:79], v[16:19], v[50:53], v[64:79]
	ds_read_b128 v[16:19], v80 offset:2048
	ds_read_b128 v[46:49], v80 offset:3072
	s_waitcnt lgkmcnt(1)
	v_mfma_f32_32x32x16_bf16 v[0:15], v[20:23], v[16:19], v[0:15]
	ds_read_b128 v[20:23], v156 offset:45184
	ds_read_b128 v[50:53], v156 offset:45312
	s_waitcnt lgkmcnt(1)
	v_mfma_f32_32x32x16_bf16 v[64:79], v[20:23], v[16:19], v[64:79]
	ds_read_b128 v[16:19], v155 offset:45184
	ds_read_b128 v[20:23], v155 offset:45312
	v_mfma_f32_32x32x16_bf16 v[0:15], v[28:31], v[46:49], v[0:15]
	s_waitcnt lgkmcnt(1)
	v_mfma_f32_32x32x16_bf16 v[64:79], v[16:19], v[46:49], v[64:79]
	ds_read_b128 v[16:19], v80 offset:4096
	ds_read_b128 v[28:31], v80 offset:5120
	s_waitcnt lgkmcnt(1)
	v_mfma_f32_32x32x16_bf16 v[0:15], v[54:57], v[16:19], v[0:15]
	ds_read_b128 v[46:49], v153 offset:45184
	ds_read_b128 v[54:57], v153 offset:45312
	s_waitcnt lgkmcnt(1)
	v_mfma_f32_32x32x16_bf16 v[64:79], v[46:49], v[16:19], v[64:79]
	v_mov_b32_e32 v46, v150
	v_mov_b32_e32 v47, v150
	v_mov_b32_e32 v48, 0
	v_mov_b32_e32 v49, v150
	v_mfma_f32_32x32x16_bf16 v[0:15], v[42:45], v[28:31], v[0:15]
	v_mov_b32_e32 v42, v150
	v_mov_b32_e32 v43, v150
	v_mov_b32_e32 v44, v150
	v_mov_b32_e32 v45, v150
	v_mfma_f32_32x32x16_bf16 v[64:79], v[38:41], v[28:31], v[64:79]
	ds_read_b128 v[16:19], v80 offset:6144
	ds_read_b128 v[28:31], v80 offset:7168
	v_mov_b32_e32 v38, v150
	v_mov_b32_e32 v39, v150
	v_mov_b32_e32 v40, v150
	v_mov_b32_e32 v41, v150
	s_waitcnt lgkmcnt(1)
	v_mfma_f32_32x32x16_bf16 v[0:15], v[24:27], v[16:19], v[0:15]
	v_mov_b32_e32 v24, v150
	v_mov_b32_e32 v25, v150
	v_mov_b32_e32 v26, v150
	v_mov_b32_e32 v27, v150
	s_waitcnt lgkmcnt(0)
	v_mfma_f32_32x32x16_bf16 v[0:15], v[34:37], v[28:31], v[0:15]
	v_mov_b32_e32 v34, v150
	v_mov_b32_e32 v35, v150
	v_mov_b32_e32 v36, v150
	v_mov_b32_e32 v37, v150
	v_mfma_f32_32x32x16_bf16 v[64:79], v[50:53], v[16:19], v[64:79]
	ds_read_b128 v[16:19], v80 offset:8192
	v_mov_b32_e32 v50, v150
	v_mov_b32_e32 v51, v150
	v_mov_b32_e32 v52, v150
	v_mov_b32_e32 v53, v150
	s_waitcnt lgkmcnt(0)
	v_mfma_f32_32x32x16_bf16 v[0:15], v[58:61], v[16:19], v[0:15]
	v_mov_b32_e32 v58, v150
	v_mov_b32_e32 v59, v150
	v_mov_b32_e32 v60, v150
	v_mov_b32_e32 v61, v150
	v_mfma_f32_32x32x16_bf16 v[64:79], v[20:23], v[28:31], v[64:79]
	s_nop 6
	v_exp_f32_e32 v149, v9
	v_mov_b32_e32 v9, v161
	v_exp_f32_e32 v176, v0
	v_exp_f32_e32 v178, v1
	v_lshlrev_b32_e32 v0, 3, v9
	v_and_b32_e32 v0, 0x78, v0
	v_lshlrev_b32_e32 v1, 5, v9
	v_and_or_b32 v0, v1, s24, v0
	v_mul_hi_i32 v1, v9, s82
	v_exp_f32_e32 v174, v2
	v_lshrrev_b32_e32 v2, 31, v1
	v_ashrrev_i32_e32 v1, 2, v1
	v_exp_f32_e32 v147, v8
	v_add_u32_e32 v8, v1, v2
	v_exp_f32_e32 v145, v10
	v_exp_f32_e32 v148, v11
	v_mul_lo_u32 v10, v8, 24
	v_lshrrev_b32_e32 v11, 3, v8
	v_sub_u32_e32 v10, v9, v10
	v_bitop3_b32 v8, v11, v8, 1 bitop3:0x6c
	v_bitop3_b32 v10, v8, v10, 7 bitop3:0x6c
	v_mul_lo_u32 v8, v8, s85
	v_lshl_add_u32 v8, v10, 3, v8
	v_add_u32_e32 v10, 0x200, v9
	v_mul_hi_i32 v11, v10, s82
	v_exp_f32_e32 v143, v12
	v_lshrrev_b32_e32 v12, 31, v11
	v_ashrrev_i32_e32 v11, 2, v11
	v_add_u32_e32 v11, v11, v12
	v_mul_lo_u32 v12, v11, 24
	v_sub_u32_e32 v10, v10, v12
	v_lshrrev_b32_e32 v12, 3, v11
	v_bitop3_b32 v11, v12, v11, 1 bitop3:0x6c
	v_bitop3_b32 v10, v11, v10, 7 bitop3:0x6c
	v_mul_lo_u32 v11, v11, s85
	v_add_u32_e32 v9, 0x400, v9
	v_lshl_add_u32 v10, v10, 3, v11
	v_mul_hi_i32 v11, v9, s82
	v_lshrrev_b32_e32 v12, 31, v11
	v_ashrrev_i32_e32 v11, 2, v11
	v_add_u32_e32 v11, v11, v12
	v_mul_lo_u32 v12, v11, 24
	v_sub_u32_e32 v9, v9, v12
	v_lshrrev_b32_e32 v12, 3, v11
	v_bitop3_b32 v11, v12, v11, 1 bitop3:0x6c
	v_bitop3_b32 v9, v11, v9, 7 bitop3:0x6c
	v_mul_lo_u32 v11, v11, s85
	v_lshl_add_u32 v12, v9, 3, v11
	v_ashrrev_i32_e32 v9, 31, v8
	v_exp_f32_e32 v172, v4
	v_add_u32_e32 v4, 0x4000, v0
	v_ashrrev_i32_e32 v1, 31, v0
	v_lshl_add_u64 v[8:9], v[8:9], 1, s[74:75]
	v_ashrrev_i32_e32 v11, 31, v10
	v_exp_f32_e32 v175, v5
	v_lshl_add_u64 v[0:1], v[0:1], 1, s[72:73]
	v_ashrrev_i32_e32 v5, 31, v4
	global_load_lds_dwordx4 v[8:9], off
	v_lshl_add_u64 v[8:9], v[10:11], 1, s[74:75]
	v_add_u32_e32 v10, 0x10000, v63
	v_exp_f32_e32 v177, v3
	global_load_dwordx4 v[0:3], v[0:1], off
	v_lshl_add_u64 v[4:5], v[4:5], 1, s[72:73]
	v_readfirstlane_b32 s21, v10
	v_add_u32_e32 v10, 0x12000, v63
	v_exp_f32_e32 v171, v6
	v_exp_f32_e32 v173, v7
	v_exp_f32_e32 v146, v13
	global_load_dwordx4 v[4:7], v[4:5], off
	s_mov_b32 m0, s21
	v_ashrrev_i32_e32 v13, 31, v12
	v_readfirstlane_b32 s21, v10
	global_load_lds_dwordx4 v[8:9], off
	v_lshl_add_u64 v[8:9], v[12:13], 1, s[74:75]
	s_mov_b32 m0, s21
	s_mov_b32 s21, s27
	global_load_lds_dwordx4 v[8:9], off
	v_mov_b32_e32 v8, v161
	s_waitcnt vmcnt(0)
	s_lshl_b64 s[72:73], s[20:21], 8
	v_ashrrev_i32_e32 v9, 4, v8
	v_and_b32_e32 v11, 0xfffff0, v9
	v_lshlrev_b32_e32 v12, 1, v9
	v_mfma_f32_32x32x16_bf16 v[64:79], v[54:57], v[16:19], v[64:79]
	v_add_u32_e32 v10, 32, v9
	v_and_or_b32 v11, v12, 8, v11
	v_lshrrev_b32_e32 v12, 1, v9
	v_and_b32_e32 v9, 3, v9
	s_add_u32 s21, s22, s72
	v_and_or_b32 v9, v12, 4, v9
	v_and_b32_e32 v12, 0xfffff0, v10
	v_lshlrev_b32_e32 v10, 1, v10
	s_addc_u32 s22, s23, s73
	v_lshrrev_b32_e32 v11, 1, v11
	v_bfe_u32 v13, v8, 2, 2
	v_and_or_b32 v10, v10, 8, v12
	s_add_u32 s36, s30, s21
	v_or_b32_e32 v11, v11, v13
	v_lshlrev_b32_e32 v8, 4, v8
	v_lshrrev_b32_e32 v10, 1, v10
	s_addc_u32 s54, s31, s22
	s_mul_hi_u32 s21, s20, 0x180
	s_mulk_i32 s20, 0x180
	v_lshlrev_b32_e32 v20, 1, v62
	v_lshlrev_b32_e32 v21, 3, v33
	v_and_b32_e32 v22, 0xc0, v162
	v_exp_f32_e32 v142, v14
	v_exp_f32_e32 v144, v15
	v_lshlrev_b32_e32 v11, 9, v11
	v_lshlrev_b32_e32 v9, 6, v9
	v_and_b32_e32 v8, 48, v8
	v_or_b32_e32 v10, v10, v13
	s_add_u32 s20, s83, s20
	v_and_b32_e32 v20, 32, v20
	v_and_b32_e32 v23, 0x100, v21
	v_and_or_b32 v21, v21, 24, v22
	v_lshlrev_b32_e32 v10, 9, v10
	v_or3_b32 v11, v11, v9, v8
	s_addc_u32 s21, s55, s21
	v_or3_b32 v151, v21, v20, v23
	s_add_u32 s55, s30, s20
	v_or_b32_e32 v128, 0x4000, v151
	s_addc_u32 s83, s31, s21
	v_mov_b32_e32 v12, v150
	v_mov_b32_e32 v13, v150
	v_mov_b32_e32 v14, v150
	v_mov_b32_e32 v15, v150
	v_mov_b32_e32 v16, 0
	v_mov_b32_e32 v17, v150
	v_mov_b32_e32 v18, v150
	v_mov_b32_e32 v19, v150
	v_mov_b32_e32 v20, v150
	v_mov_b32_e32 v21, v150
	v_mov_b32_e32 v22, v150
	v_mov_b32_e32 v23, v150
	v_mov_b32_e32 v28, v150
	v_mov_b32_e32 v29, v150
	v_mov_b32_e32 v30, v150
	s_waitcnt vmcnt(0)
	ds_write_b128 v11, v[0:3] offset:16384
	v_or3_b32 v0, v10, v9, v8
	v_mov_b32_e32 v1, v150
	v_mov_b32_e32 v2, v150
	v_mov_b32_e32 v3, v150
	v_mov_b32_e32 v8, v150
	v_mov_b32_e32 v9, v150
	ds_write_b128 v0, v[4:7] offset:16384
	v_mov_b32_e32 v0, 0
	v_mov_b32_e32 v4, v150
	v_mov_b32_e32 v5, v150
	v_mov_b32_e32 v6, v150
	v_mov_b32_e32 v7, v150
	v_mov_b32_e32 v10, v150
	v_mov_b32_e32 v11, v150
	v_mov_b32_e32 v31, v150
	v_mov_b32_e32 v33, v150
	v_mov_b32_e32 v54, v150
	v_mov_b32_e32 v55, v150
	v_mov_b32_e32 v56, v150
	v_mov_b32_e32 v57, v150
	v_mov_b32_e32 v62, v150
	v_mov_b32_e32 v63, v150
	v_mov_b32_e32 v97, v161
	v_mul_hi_i32 v99, v97, s82
	v_lshrrev_b32_e32 v100, 31, v99
	v_ashrrev_i32_e32 v99, 2, v99
	v_add_u32_e32 v99, v99, v100
	v_mul_lo_u32 v100, v99, 24
	v_lshrrev_b32_e32 v101, 3, v99
	v_sub_u32_e32 v100, v97, v100
	v_bitop3_b32 v99, v101, v99, 1 bitop3:0x6c
	v_bitop3_b32 v100, v99, v100, 7 bitop3:0x6c
	v_mul_lo_u32 v99, v99, s85
	v_lshl_add_u32 v100, v100, 3, v99
	v_add_u32_e32 v99, 0x200, v97
	v_mul_hi_i32 v101, v99, s82
	v_lshrrev_b32_e32 v102, 31, v101
	v_ashrrev_i32_e32 v101, 2, v101
	v_add_u32_e32 v101, v101, v102
	v_mul_lo_u32 v102, v101, 24
	v_sub_u32_e32 v99, v99, v102
	v_lshrrev_b32_e32 v102, 3, v101
	v_bitop3_b32 v101, v102, v101, 1 bitop3:0x6c
	v_lshlrev_b32_e32 v96, 3, v97
	v_lshlrev_b32_e32 v98, 5, v97
	v_bitop3_b32 v99, v101, v99, 7 bitop3:0x6c
	v_mul_lo_u32 v101, v101, s85
	v_add_u32_e32 v97, 0x400, v97
	v_lshl_add_u32 v102, v99, 3, v101
	v_mul_hi_i32 v99, v97, s82
	v_lshrrev_b32_e32 v101, 31, v99
	v_ashrrev_i32_e32 v99, 2, v99
	v_add_u32_e32 v99, v99, v101
	v_mul_lo_u32 v101, v99, 24
	v_sub_u32_e32 v97, v97, v101
	v_lshrrev_b32_e32 v101, 3, v99
	v_bitop3_b32 v99, v101, v99, 1 bitop3:0x6c
	v_bitop3_b32 v97, v99, v97, 7 bitop3:0x6c
	v_mul_lo_u32 v99, v99, s85
	v_ashrrev_i32_e32 v101, 31, v100
	v_and_b32_e32 v96, 0x78, v96
	v_lshl_add_u32 v104, v97, 3, v99
	v_and_or_b32 v96, v98, s24, v96
	v_lshlrev_b32_e32 v235, 1, v100
	v_lshlrev_b32_e32 v236, 1, v102
	v_lshlrev_b32_e32 v237, 1, v104
	v_lshlrev_b32_e32 v232, 1, v96
	s_waitcnt lgkmcnt(0)
	s_barrier
; #define SBAR() __builtin_amdgcn_sched_barrier(0)
; #define QKT(P0, P1, BUF) qkt<DQK, QL>(P0, P1, shm + K_OFF + (BUF) * SHM_K, qr, qlds, kofs, negM)
; template <int DQK, int QL>
; __device__ __forceinline__ void qkt(f32x16& p0, f32x16& p1, const char* Ks, const bf16x8 (&qr)[DQK / 16 - QL], const char* qlds, const int (&kofs)[4], float negM) {
;   constexpr int QR = DQK / 16 - QL;
; #pragma unroll
;   for (int r = 0; r < 16; ++r) { p0[r] = negM; p1[r] = negM; }
; #pragma unroll
;   for (int d0 = 0; d0 < DQK / 16; ++d0) {
;     const char* kp = Ks + kofs[d0 & 3] + (d0 >> 2) * 128;
;     bf16x8 b0 = *reinterpret_cast<const bf16x8*>(kp);
;     bf16x8 b1 = *reinterpret_cast<const bf16x8*>(kp + 32 * DQK * 2);
;     bf16x8 qf;
;     if constexpr (QL > 0) { if (d0 < QR) qf = qr[d0 < QR ? d0 : 0]; else qf = *reinterpret_cast<const bf16x8*>(qlds + (d0 - QR) * 1024); }
;     else qf = qr[d0];
;     p0 = __builtin_amdgcn_mfma_f32_32x32x16_bf16(b0, qf, p0, 0, 0, 0);
;     p1 = __builtin_amdgcn_mfma_f32_32x32x16_bf16(b1, qf, p1, 0, 0, 0);
;   }
; }
;     ...
;     if constexpr (ONEP) { finishSM(pA0, pA1, l_reg, pa0, pa1, pa2, pa3); SBAR(); QKT(pB0, pB1, 1); }
;     else { QKT(pB0, pB1, 1); finishSM(pA0, pA1, l_reg, pa0, pa1, pa2, pa3); }
;     SBAR();
;     SLOAD(TKEY(j + 1), 0); SBAR();
.LBB0_369:
	v_add_f32_e32 v80, 0, v176
	v_add_f32_e32 v80, v178, v80
	v_add_f32_e32 v80, v174, v80
	v_add_f32_e32 v80, v177, v80
	v_add_f32_e32 v80, v172, v80
	v_add_f32_e32 v80, v175, v80
	v_add_f32_e32 v80, v171, v80
	v_add_f32_e32 v80, v173, v80
	v_add_f32_e32 v80, v147, v80
	v_add_f32_e32 v80, v149, v80
	v_add_f32_e32 v80, v145, v80
	v_add_f32_e32 v80, v148, v80
	v_exp_f32_e32 v64, v64
	v_add_f32_e32 v80, v143, v80
	v_exp_f32_e32 v65, v65
	v_add_f32_e32 v80, v146, v80
	v_exp_f32_e32 v66, v66
	v_add_f32_e32 v80, v142, v80
	v_exp_f32_e32 v67, v67
	v_add_f32_e32 v80, v144, v80
	v_exp_f32_e32 v68, v68
	v_add_f32_e32 v80, v64, v80
	v_exp_f32_e32 v69, v69
	v_add_f32_e32 v80, v65, v80
	v_exp_f32_e32 v70, v70
	v_add_f32_e32 v80, v66, v80
	v_exp_f32_e32 v71, v71
	v_add_f32_e32 v80, v67, v80
	v_exp_f32_e32 v72, v72
	v_add_f32_e32 v80, v68, v80
	v_exp_f32_e32 v73, v73
	v_add_f32_e32 v80, v69, v80
	v_exp_f32_e32 v74, v74
	v_add_f32_e32 v80, v70, v80
	v_exp_f32_e32 v75, v75
	v_add_f32_e32 v80, v71, v80
	v_exp_f32_e32 v76, v76
	v_add_f32_e32 v80, v72, v80
	v_exp_f32_e32 v77, v77
	v_add_f32_e32 v80, v73, v80
	v_exp_f32_e32 v78, v78
	v_add_f32_e32 v80, v74, v80
	v_exp_f32_e32 v79, v79
	v_add_f32_e32 v80, v75, v80
	v_add_f32_e32 v80, v76, v80
	v_add_f32_e32 v80, v77, v80
	v_add_f32_e32 v80, v78, v80
	v_add_f32_e32 v169, v79, v80
	v_mov_b32_e32 v170, v169
	s_nop 1
	v_permlane32_swap_b32_e32 v169, v170
	v_cvt_pk_bf16_f32 v120, v176, v178
	v_cvt_pk_bf16_f32 v121, v174, v177
	v_cvt_pk_bf16_f32 v122, v172, v175
	v_cvt_pk_bf16_f32 v123, v171, v173
	v_cvt_pk_bf16_f32 v124, v147, v149
	v_cvt_pk_bf16_f32 v125, v145, v148
	v_cvt_pk_bf16_f32 v126, v143, v146
	v_cvt_pk_bf16_f32 v127, v142, v144
	v_cvt_pk_bf16_f32 v142, v64, v65
	v_cvt_pk_bf16_f32 v143, v66, v67
	v_cvt_pk_bf16_f32 v144, v68, v69
	v_cvt_pk_bf16_f32 v145, v70, v71
	v_cvt_pk_bf16_f32 v146, v72, v73
	v_cvt_pk_bf16_f32 v147, v74, v75
	v_cvt_pk_bf16_f32 v148, v76, v77
	v_cvt_pk_bf16_f32 v149, v78, v79
	s_nop 0
	v_permlane32_swap_b32_e32 v120, v122
	v_permlane32_swap_b32_e32 v121, v123
	v_permlane32_swap_b32_e32 v124, v126
	v_permlane32_swap_b32_e32 v125, v127
	v_permlane32_swap_b32_e32 v142, v144
	v_permlane32_swap_b32_e32 v143, v145
	v_permlane32_swap_b32_e32 v146, v148
	v_permlane32_swap_b32_e32 v147, v149
	ds_read_b128 v[80:83], v152 offset:57344
	ds_read_b128 v[84:87], v152 offset:57472
	v_mov_b64_e32 v[110:111], s[18:19]
	v_mov_b64_e32 v[108:109], s[16:17]
	v_mov_b64_e32 v[106:107], s[14:15]
	v_mov_b64_e32 v[104:105], s[12:13]
	v_mov_b64_e32 v[102:103], s[10:11]
	v_mov_b64_e32 v[100:101], s[8:9]
	v_mov_b64_e32 v[98:99], s[6:7]
	v_mov_b64_e32 v[96:97], s[4:5]
	v_add_u32_e32 v167, v163, v162
	s_waitcnt lgkmcnt(1)
	v_mfma_f32_32x32x16_bf16 v[64:79], v[80:83], v[138:141], v[96:111]
	ds_read_b128 v[80:83], v156 offset:57344
	ds_read_b128 v[88:91], v152 offset:57600
	s_waitcnt lgkmcnt(1)
	v_mfma_f32_32x32x16_bf16 v[64:79], v[80:83], v[134:137], v[64:79]
	ds_read_b128 v[80:83], v155 offset:57344
	ds_read_b128 v[92:95], v155 offset:57472
	s_waitcnt lgkmcnt(1)
	v_mfma_f32_32x32x16_bf16 v[64:79], v[80:83], v[130:133], v[64:79]
	ds_read_b128 v[80:83], v153 offset:57344
	ds_read_b128 v[112:115], v167
	ds_read_b128 v[116:119], v155 offset:57600
	ds_read_b128 v[172:175], v167 offset:1024
	s_waitcnt lgkmcnt(2)
	v_mfma_f32_32x32x16_bf16 v[64:79], v[80:83], v[112:115], v[64:79]
	s_waitcnt lgkmcnt(0)
	v_mfma_f32_32x32x16_bf16 v[64:79], v[84:87], v[172:175], v[64:79]
	ds_read_b128 v[80:83], v156 offset:57472
	ds_read_b128 v[176:179], v167 offset:2048
	ds_read_b128 v[84:87], v156 offset:57600
	ds_read_b128 v[180:183], v167 offset:3072
	s_waitcnt lgkmcnt(2)
	v_mfma_f32_32x32x16_bf16 v[64:79], v[80:83], v[176:179], v[64:79]
	s_waitcnt lgkmcnt(0)
	v_mfma_f32_32x32x16_bf16 v[64:79], v[92:95], v[180:183], v[64:79]
	ds_read_b128 v[80:83], v153 offset:57472
	ds_read_b128 v[184:187], v167 offset:4096
	ds_read_b128 v[188:191], v167 offset:5120
	ds_read_b128 v[92:95], v153 offset:57600
	ds_read_b128 v[192:195], v167 offset:6144
	ds_read_b128 v[196:199], v167 offset:7168
	ds_read_b128 v[200:203], v160 offset:12288
	ds_read_b128 v[204:207], v160 offset:12416
	ds_read_b128 v[208:211], v158 offset:12288
	ds_read_b128 v[212:215], v158 offset:12416
	ds_read_b128 v[216:219], v159 offset:12288
	ds_read_b128 v[220:223], v160 offset:12544
	s_waitcnt lgkmcnt(10)
	v_mfma_f32_32x32x16_bf16 v[64:79], v[80:83], v[184:187], v[64:79]
	s_waitcnt lgkmcnt(9)
	v_mfma_f32_32x32x16_bf16 v[64:79], v[88:91], v[188:191], v[64:79]
	s_waitcnt lgkmcnt(7)
	v_mfma_f32_32x32x16_bf16 v[64:79], v[84:87], v[192:195], v[64:79]
	s_waitcnt lgkmcnt(6)
	v_mfma_f32_32x32x16_bf16 v[64:79], v[116:119], v[196:199], v[64:79]
	ds_read_b128 v[116:119], v159 offset:12416
	ds_read_b128 v[238:241], v159 offset:12544
	ds_read_b128 v[242:245], v167 offset:8192
	ds_read_b128 v[246:249], v157 offset:12288
	ds_read_b128 v[250:253], v158 offset:12544
	ds_read_b128 v[228:231], v157 offset:12416
	ds_read_b128 v[224:227], v157 offset:12544
	s_waitcnt lgkmcnt(4)
	v_mfma_f32_32x32x16_bf16 v[64:79], v[92:95], v[242:245], v[64:79]
	v_mfma_f32_32x32x16_bf16 v[80:95], v[200:203], v[138:141], v[96:111]
	v_mov_b32_e32 v171, v161
	s_add_u32 s72, s55, s0
	s_addc_u32 s73, s83, s1
	v_mfma_f32_32x32x16_bf16 v[80:95], v[216:219], v[134:137], v[80:95]
	v_mfma_f32_32x32x16_bf16 v[80:95], v[208:211], v[130:133], v[80:95]
	s_waitcnt lgkmcnt(3)
; #define WAIT_L0() asm volatile("s_waitcnt lgkmcnt(0)" ::: "memory")
; #define SBAR() __builtin_amdgcn_sched_barrier(0)
; template <int NCB, int D0> __device__ __forceinline__ void pv_one(f32x16& od, int vb, bf16x8 pa0, bf16x8 pa1, bf16x8 pa2, bf16x8 pa3) {
;   constexpr int KSTEP = NCB * 1024, HALF = NCB * 512, B0 = D0 * 512;
;   const s16x4 l0 = tr_read<B0>(vb), h0 = tr_read<B0 + HALF>(vb), l1 = tr_read<B0 + KSTEP>(vb), h1 = tr_read<B0 + KSTEP + HALF>(vb);
;   const s16x4 l2 = tr_read<B0 + 2 * KSTEP>(vb), h2 = tr_read<B0 + 2 * KSTEP + HALF>(vb), l3 = tr_read<B0 + 3 * KSTEP>(vb), h3 = tr_read<B0 + 3 * KSTEP + HALF>(vb);
;   WAIT_L0(); SBAR();
;     ...
;   od = __builtin_amdgcn_mfma_f32_32x32x16_bf16(pa0, PK(l0, h0), od, 0, 0, 0);
;   od = __builtin_amdgcn_mfma_f32_32x32x16_bf16(pa1, PK(l1, h1), od, 0, 0, 0);
;   od = __builtin_amdgcn_mfma_f32_32x32x16_bf16(pa2, PK(l2, h2), od, 0, 0, 0);
;   od = __builtin_amdgcn_mfma_f32_32x32x16_bf16(pa3, PK(l3, h3), od, 0, 0, 0);
;     ...
; }
; template <int NCB> __device__ __forceinline__ void pv_all(f32x16 (&o)[NCB], int vb, bf16x8 pa0, bf16x8 pa1, bf16x8 pa2, bf16x8 pa3) {
;   pv_one<NCB, 0>(o[0], vb, pa0, pa1, pa2, pa3); pv_one<NCB, 1>(o[1], vb, pa0, pa1, pa2, pa3);
;   if constexpr (NCB == 4) { pv_one<NCB, 2>(o[2], vb, pa0, pa1, pa2, pa3); pv_one<NCB, 3>(o[3], vb, pa0, pa1, pa2, pa3); }
;     ...
;     SLOAD(TKEY(j + 1), 0); SBAR();
;     pv_all<NCB>(o, vb0, pa0, pa1, pa2, pa3);
	v_mfma_f32_32x32x16_bf16 v[80:95], v[246:249], v[112:115], v[80:95]
	v_mfma_f32_32x32x16_bf16 v[80:95], v[204:207], v[172:175], v[80:95]
	s_add_u32 s74, s36, s0
	s_addc_u32 s75, s54, s1
	s_add_u32 s100, s72, s46
	s_addc_u32 s101, s73, s47
	v_readfirstlane_b32 s20, v164
	s_mov_b32 m0, s20
	s_nop 0
	global_load_lds_dwordx4 v235, s[100:101]
	v_readfirstlane_b32 s20, v165
	s_mov_b32 m0, s20
	s_nop 0
	global_load_lds_dwordx4 v236, s[100:101]
	v_readfirstlane_b32 s20, v166
	s_mov_b32 m0, s20
	s_nop 0
	global_load_lds_dwordx4 v237, s[100:101]
	v_mfma_f32_32x32x16_bf16 v[80:95], v[116:119], v[176:179], v[80:95]
	s_add_u32 s100, s74, s25
	s_addc_u32 s101, s75, 0
	global_load_dwordx4 v[112:115], v232, s[100:101] offset:256
	s_add_u32 s100, s100, 0x8000
	s_addc_u32 s101, s101, 0
	global_load_dwordx4 v[116:119], v232, s[100:101] offset:256
	v_mfma_f32_32x32x16_bf16 v[80:95], v[212:215], v[180:183], v[80:95]
	s_waitcnt lgkmcnt(0)
	v_mfma_f32_32x32x16_bf16 v[80:95], v[228:231], v[184:187], v[80:95]
	v_mfma_f32_32x32x16_bf16 v[80:95], v[220:223], v[188:191], v[80:95]
	v_mfma_f32_32x32x16_bf16 v[80:95], v[238:241], v[192:195], v[80:95]
	v_mfma_f32_32x32x16_bf16 v[80:95], v[250:253], v[196:199], v[80:95]
	v_mfma_f32_32x32x16_bf16 v[80:95], v[224:227], v[242:245], v[80:95]
	ds_read_b64_tr_b16 v[96:97], v151 offset:0
	ds_read_b64_tr_b16 v[98:99], v151 offset:0x800
	ds_read_b64_tr_b16 v[100:101], v151 offset:0x1000
	ds_read_b64_tr_b16 v[102:103], v151 offset:0x1800
	ds_read_b64_tr_b16 v[104:105], v151 offset:0x2000
	ds_read_b64_tr_b16 v[106:107], v151 offset:0x2800
	ds_read_b64_tr_b16 v[108:109], v151 offset:0x3000
	ds_read_b64_tr_b16 v[110:111], v151 offset:0x3800
	s_nop 0
	s_waitcnt lgkmcnt(6)
	v_mfma_f32_32x32x16_bf16 v[0:15], v[120:123], v[96:99], v[0:15]
	ds_read_b64_tr_b16 v[96:97], v151 offset:0x200
	ds_read_b64_tr_b16 v[98:99], v151 offset:0xa00
	s_waitcnt lgkmcnt(6)
	v_mfma_f32_32x32x16_bf16 v[0:15], v[124:127], v[100:103], v[0:15]
	ds_read_b64_tr_b16 v[100:101], v151 offset:0x1200
	ds_read_b64_tr_b16 v[102:103], v151 offset:0x1a00
	s_waitcnt lgkmcnt(6)
	v_mfma_f32_32x32x16_bf16 v[0:15], v[142:145], v[104:107], v[0:15]
	ds_read_b64_tr_b16 v[104:105], v151 offset:0x2200
	ds_read_b64_tr_b16 v[106:107], v151 offset:0x2a00
	s_waitcnt lgkmcnt(6)
	v_mfma_f32_32x32x16_bf16 v[0:15], v[146:149], v[108:111], v[0:15]
	ds_read_b64_tr_b16 v[108:109], v151 offset:0x3200
	ds_read_b64_tr_b16 v[110:111], v151 offset:0x3a00
	s_waitcnt lgkmcnt(6)
	v_mfma_f32_32x32x16_bf16 v[16:31], v[120:123], v[96:99], v[16:31]
	ds_read_b64_tr_b16 v[96:97], v151 offset:0x400
	ds_read_b64_tr_b16 v[98:99], v151 offset:0xc00
	s_waitcnt lgkmcnt(6)
	v_mfma_f32_32x32x16_bf16 v[16:31], v[124:127], v[100:103], v[16:31]
	ds_read_b64_tr_b16 v[100:101], v151 offset:0x1400
	ds_read_b64_tr_b16 v[102:103], v151 offset:0x1c00
	s_waitcnt lgkmcnt(6)
	v_mfma_f32_32x32x16_bf16 v[16:31], v[142:145], v[104:107], v[16:31]
	ds_read_b64_tr_b16 v[104:105], v151 offset:0x2400
	ds_read_b64_tr_b16 v[106:107], v151 offset:0x2c00
	s_waitcnt lgkmcnt(6)
	v_mfma_f32_32x32x16_bf16 v[16:31], v[146:149], v[108:111], v[16:31]
	ds_read_b64_tr_b16 v[108:109], v151 offset:0x3400
	ds_read_b64_tr_b16 v[110:111], v151 offset:0x3c00
	s_waitcnt lgkmcnt(6)
	v_mfma_f32_32x32x16_bf16 v[32:47], v[120:123], v[96:99], v[32:47]
	ds_read_b64_tr_b16 v[96:97], v151 offset:0x600
	ds_read_b64_tr_b16 v[98:99], v151 offset:0xe00
	s_waitcnt lgkmcnt(6)
	v_mfma_f32_32x32x16_bf16 v[32:47], v[124:127], v[100:103], v[32:47]
	ds_read_b64_tr_b16 v[100:101], v151 offset:0x1600
	ds_read_b64_tr_b16 v[102:103], v151 offset:0x1e00
	s_waitcnt lgkmcnt(6)
	v_mfma_f32_32x32x16_bf16 v[32:47], v[142:145], v[104:107], v[32:47]
	ds_read_b64_tr_b16 v[104:105], v151 offset:0x2600
	ds_read_b64_tr_b16 v[106:107], v151 offset:0x2e00
	s_waitcnt lgkmcnt(6)
	v_mfma_f32_32x32x16_bf16 v[32:47], v[146:149], v[108:111], v[32:47]
	ds_read_b64_tr_b16 v[108:109], v151 offset:0x3600
	ds_read_b64_tr_b16 v[110:111], v151 offset:0x3e00
	s_waitcnt lgkmcnt(6)
	v_mfma_f32_32x32x16_bf16 v[48:63], v[120:123], v[96:99], v[48:63]
	s_add_i32 s20, s87, 64
	s_cmp_le_i32 s20, s59
	v_add_u32_e32 v171, s87, v154
	s_waitcnt lgkmcnt(4)
	v_mfma_f32_32x32x16_bf16 v[48:63], v[124:127], v[100:103], v[48:63]
	s_waitcnt lgkmcnt(2)
	v_mfma_f32_32x32x16_bf16 v[48:63], v[142:145], v[104:107], v[48:63]
	s_waitcnt lgkmcnt(0)
	v_mfma_f32_32x32x16_bf16 v[48:63], v[146:149], v[108:111], v[48:63]
	s_cbranch_scc1 .LBB0_371
; #define WAIT_V0() asm volatile("s_waitcnt vmcnt(0)" ::: "memory")
; __device__ __forceinline__ int crow(int r, int hi) { return (r & 3) + 8 * (r >> 2) + 4 * hi; }
; #define SWRITE(b) do { FRESH_COORDS(); \
;     if constexpr (!KDMA) { _Pragma("unroll") for (int i = 0; i < KC; ++i) *reinterpret_cast<bf16x8*>(shm + (b) * SHM_K + klo[i]) = ks[i]; } \
;     _Pragma("unroll") for (int i = 0; i < VC; ++i) *reinterpret_cast<bf16x8*>(shm + (b) * SHM_V + vlo[i]) = vs[i]; } while (0)
; template <bool GM>
; __device__ __forceinline__ void partialSM(f32x16& p0, f32x16& p1, bool mask, int kbase, int L, int qpos, int hi) {
;   if (mask) {
; #pragma unroll
;     for (int r = 0; r < 16; ++r) {
;       int k = kbase + crow(r, hi);
;       asm volatile("" : "+v"(k) : "v"(p0[r]));
;       bool ok = k < L;
;       if (GM) ok = ok && (k < 16 || abs(qpos - k) <= 128);
;       p0[r] = ok ? p0[r] : -1e30f;
;       int k2 = k + 32;
;       asm volatile("" : "+v"(k2) : "v"(p1[r]));
;       bool ok2 = k2 < L;
;       if (GM) ok2 = ok2 && (k2 < 16 || abs(qpos - k2) <= 128);
;       p1[r] = ok2 ? p1[r] : -1e30f;
;     }
;   }
; #pragma unroll
;   for (int r = 0; r < 16; ++r) p0[r] = __builtin_amdgcn_exp2f(p0[r]);
; }
;     ...
;     partialSM<GM>(pB0, pB1, NEEDMASK(kb), kb, L, qpos, hi);
;     __syncthreads(); WAIT_V0(); SWRITE(0);
	v_add_u32_e32 v96, 64, v171
	s_nop 0
	v_cmp_gt_i32_e32 vcc, s94, v96
	v_add_u32_e32 v96, 32, v96
	s_nop 0
	v_cndmask_b32_e32 v64, v233, v64, vcc
	v_cmp_gt_i32_e32 vcc, s94, v96
	v_add_u32_e32 v96, 0x41, v171
	s_nop 0
	v_cndmask_b32_e32 v80, v233, v80, vcc
	v_cmp_gt_i32_e32 vcc, s94, v96
	v_add_u32_e32 v96, 32, v96
	s_nop 0
	v_cndmask_b32_e32 v65, v233, v65, vcc
	v_cmp_gt_i32_e32 vcc, s94, v96
	v_add_u32_e32 v96, 0x42, v171
	s_nop 0
	v_cndmask_b32_e32 v81, v233, v81, vcc
	v_cmp_gt_i32_e32 vcc, s94, v96
	v_add_u32_e32 v96, 32, v96
	s_nop 0
	v_cndmask_b32_e32 v66, v233, v66, vcc
	v_cmp_gt_i32_e32 vcc, s94, v96
	v_add_u32_e32 v96, 0x43, v171
	s_nop 0
	v_cndmask_b32_e32 v82, v233, v82, vcc
	v_cmp_gt_i32_e32 vcc, s94, v96
	v_add_u32_e32 v96, 32, v96
	s_nop 0
	v_cndmask_b32_e32 v67, v233, v67, vcc
	v_cmp_gt_i32_e32 vcc, s94, v96
	v_add_u32_e32 v96, 0x48, v171
	s_nop 0
	v_cndmask_b32_e32 v83, v233, v83, vcc
	v_cmp_gt_i32_e32 vcc, s94, v96
	v_add_u32_e32 v96, 32, v96
	s_nop 0
	v_cndmask_b32_e32 v68, v233, v68, vcc
	v_cmp_gt_i32_e32 vcc, s94, v96
	v_add_u32_e32 v96, 0x49, v171
	s_nop 0
	v_cndmask_b32_e32 v84, v233, v84, vcc
	v_cmp_gt_i32_e32 vcc, s94, v96
	v_add_u32_e32 v96, 32, v96
	s_nop 0
	v_cndmask_b32_e32 v69, v233, v69, vcc
	v_cmp_gt_i32_e32 vcc, s94, v96
	v_add_u32_e32 v96, 0x4a, v171
	s_nop 0
	v_cndmask_b32_e32 v85, v233, v85, vcc
	v_cmp_gt_i32_e32 vcc, s94, v96
	v_add_u32_e32 v96, 32, v96
	s_nop 0
	v_cndmask_b32_e32 v70, v233, v70, vcc
	v_cmp_gt_i32_e32 vcc, s94, v96
	v_add_u32_e32 v96, 0x4b, v171
	s_nop 0
	v_cndmask_b32_e32 v86, v233, v86, vcc
	v_cmp_gt_i32_e32 vcc, s94, v96
	v_add_u32_e32 v96, 32, v96
	s_nop 0
	v_cndmask_b32_e32 v71, v233, v71, vcc
	v_cmp_gt_i32_e32 vcc, s94, v96
	v_add_u32_e32 v96, 0x50, v171
	s_nop 0
	v_cndmask_b32_e32 v87, v233, v87, vcc
	v_cmp_gt_i32_e32 vcc, s94, v96
	v_add_u32_e32 v96, 32, v96
	s_nop 0
	v_cndmask_b32_e32 v72, v233, v72, vcc
	v_cmp_gt_i32_e32 vcc, s94, v96
	v_add_u32_e32 v96, 0x51, v171
	s_nop 0
	v_cndmask_b32_e32 v88, v233, v88, vcc
	v_cmp_gt_i32_e32 vcc, s94, v96
	v_add_u32_e32 v96, 32, v96
	s_nop 0
	v_cndmask_b32_e32 v73, v233, v73, vcc
	v_cmp_gt_i32_e32 vcc, s94, v96
	v_add_u32_e32 v96, 0x52, v171
	s_nop 0
	v_cndmask_b32_e32 v89, v233, v89, vcc
	v_cmp_gt_i32_e32 vcc, s94, v96
	v_add_u32_e32 v96, 32, v96
	s_nop 0
	v_cndmask_b32_e32 v74, v233, v74, vcc
	v_cmp_gt_i32_e32 vcc, s94, v96
	v_add_u32_e32 v96, 0x53, v171
	s_nop 0
	v_cndmask_b32_e32 v90, v233, v90, vcc
	v_cmp_gt_i32_e32 vcc, s94, v96
	v_add_u32_e32 v96, 32, v96
	s_nop 0
	v_cndmask_b32_e32 v75, v233, v75, vcc
	v_cmp_gt_i32_e32 vcc, s94, v96
	v_add_u32_e32 v96, 0x58, v171
	s_nop 0
	v_cndmask_b32_e32 v91, v233, v91, vcc
	v_cmp_gt_i32_e32 vcc, s94, v96
	v_add_u32_e32 v96, 32, v96
	s_nop 0
	v_cndmask_b32_e32 v76, v233, v76, vcc
	v_cmp_gt_i32_e32 vcc, s94, v96
	v_add_u32_e32 v96, 0x59, v171
	s_nop 0
	v_cndmask_b32_e32 v92, v233, v92, vcc
	v_cmp_gt_i32_e32 vcc, s94, v96
	v_add_u32_e32 v96, 32, v96
	s_nop 0
	v_cndmask_b32_e32 v77, v233, v77, vcc
	v_cmp_gt_i32_e32 vcc, s94, v96
	v_add_u32_e32 v96, 0x5a, v171
	s_nop 0
	v_cndmask_b32_e32 v93, v233, v93, vcc
	v_cmp_gt_i32_e32 vcc, s94, v96
	v_add_u32_e32 v96, 32, v96
	s_nop 0
	v_cndmask_b32_e32 v78, v233, v78, vcc
	v_cmp_gt_i32_e32 vcc, s94, v96
	v_add_u32_e32 v96, 0x5b, v171
	s_nop 0
	v_cndmask_b32_e32 v94, v233, v94, vcc
	v_cmp_gt_i32_e32 vcc, s94, v96
	v_add_u32_e32 v96, 32, v96
	s_nop 0
	v_cndmask_b32_e32 v79, v233, v79, vcc
	v_cmp_gt_i32_e32 vcc, s94, v96
	s_nop 1
	v_cndmask_b32_e32 v95, v233, v95, vcc
.LBB0_371:
	v_mov_b32_e32 v96, v161
	s_waitcnt vmcnt(0)
	s_barrier
	s_waitcnt vmcnt(0)
	v_exp_f32_e32 v64, v64
	v_ashrrev_i32_e32 v97, 4, v96
	v_and_b32_e32 v99, 0xfffff0, v97
	v_lshlrev_b32_e32 v100, 1, v97
	v_add_u32_e32 v98, 32, v97
	v_and_or_b32 v99, v100, 8, v99
	v_lshrrev_b32_e32 v100, 1, v97
	v_and_b32_e32 v97, 3, v97
	v_and_or_b32 v97, v100, 4, v97
	v_and_b32_e32 v100, 0xfffff0, v98
	v_lshlrev_b32_e32 v98, 1, v98
	v_and_or_b32 v98, v98, 8, v100
	v_lshrrev_b32_e32 v99, 1, v99
	v_bfe_u32 v101, v96, 2, 2
	v_lshrrev_b32_e32 v98, 1, v98
	v_exp_f32_e32 v66, v66
	v_exp_f32_e32 v68, v68
	v_exp_f32_e32 v70, v70
	v_exp_f32_e32 v72, v72
	v_exp_f32_e32 v74, v74
	v_exp_f32_e32 v76, v76
	v_exp_f32_e32 v78, v78
	v_exp_f32_e32 v65, v65
	v_exp_f32_e32 v67, v67
	v_exp_f32_e32 v69, v69
	v_exp_f32_e32 v71, v71
	v_exp_f32_e32 v73, v73
	v_exp_f32_e32 v75, v75
	v_exp_f32_e32 v77, v77
	v_exp_f32_e32 v79, v79
	v_or_b32_e32 v99, v99, v101
	v_lshlrev_b32_e32 v96, 4, v96
	v_or_b32_e32 v98, v98, v101
	v_lshlrev_b32_e32 v99, 9, v99
	v_lshlrev_b32_e32 v97, 6, v97
	v_and_b32_e32 v96, 48, v96
	v_lshlrev_b32_e32 v98, 9, v98
	v_or3_b32 v99, v99, v97, v96
	v_or3_b32 v96, v98, v97, v96
	ds_write_b128 v99, v[112:115]
	ds_write_b128 v96, v[116:119]
	s_waitcnt lgkmcnt(0)
	s_barrier
; #define SBAR() __builtin_amdgcn_sched_barrier(0)
; #define QKT(P0, P1, BUF) qkt<DQK, QL>(P0, P1, shm + K_OFF + (BUF) * SHM_K, qr, qlds, kofs, negM)
;     ...
;     if constexpr (ONEP) { finishSM(pB0, pB1, l_reg, pa0, pa1, pa2, pa3); SBAR(); QKT(pA0, pA1, 0); }
;     else { QKT(pA0, pA1, 0); finishSM(pB0, pB1, l_reg, pa0, pa1, pa2, pa3); }
;     SBAR();
;     if (j + 2 < NT) SLOAD(TKEY(j + 2), 1);
	v_add_f32_e32 v96, 0, v64
	v_add_f32_e32 v96, v65, v96
	v_add_f32_e32 v96, v66, v96
	v_add_f32_e32 v96, v67, v96
	v_add_f32_e32 v96, v68, v96
	v_add_f32_e32 v96, v69, v96
	v_add_f32_e32 v96, v70, v96
	v_add_f32_e32 v96, v71, v96
	v_add_f32_e32 v96, v72, v96
	v_add_f32_e32 v96, v73, v96
	v_add_f32_e32 v96, v74, v96
	v_add_f32_e32 v96, v75, v96
	v_exp_f32_e32 v80, v80
	v_add_f32_e32 v96, v76, v96
	v_exp_f32_e32 v81, v81
	v_add_f32_e32 v96, v77, v96
	v_exp_f32_e32 v82, v82
	v_add_f32_e32 v96, v78, v96
	v_exp_f32_e32 v83, v83
	v_add_f32_e32 v96, v79, v96
	v_exp_f32_e32 v84, v84
	v_add_f32_e32 v96, v80, v96
	v_exp_f32_e32 v85, v85
	v_add_f32_e32 v96, v81, v96
	v_exp_f32_e32 v86, v86
	v_add_f32_e32 v96, v82, v96
	v_exp_f32_e32 v87, v87
	v_add_f32_e32 v96, v83, v96
	v_exp_f32_e32 v88, v88
	v_add_f32_e32 v96, v84, v96
	v_exp_f32_e32 v89, v89
	v_add_f32_e32 v96, v85, v96
	v_exp_f32_e32 v90, v90
	v_add_f32_e32 v96, v86, v96
	v_exp_f32_e32 v91, v91
	v_add_f32_e32 v96, v87, v96
	v_exp_f32_e32 v92, v92
	v_add_f32_e32 v96, v88, v96
	v_exp_f32_e32 v93, v93
	v_add_f32_e32 v96, v89, v96
	v_exp_f32_e32 v94, v94
	v_add_f32_e32 v96, v90, v96
	v_exp_f32_e32 v95, v95
	v_add_f32_e32 v96, v91, v96
	v_add_f32_e32 v96, v92, v96
	v_add_f32_e32 v96, v93, v96
	v_add_f32_e32 v96, v94, v96
	v_add_f32_e32 v179, v95, v96
	v_mov_b32_e32 v180, v179
	v_cvt_pk_bf16_f32 v120, v64, v65
	v_cvt_pk_bf16_f32 v121, v66, v67
	v_cvt_pk_bf16_f32 v122, v68, v69
	v_cvt_pk_bf16_f32 v123, v70, v71
	v_cvt_pk_bf16_f32 v124, v72, v73
	v_cvt_pk_bf16_f32 v125, v74, v75
	v_cvt_pk_bf16_f32 v126, v76, v77
	v_cvt_pk_bf16_f32 v127, v78, v79
	v_cvt_pk_bf16_f32 v142, v80, v81
	v_cvt_pk_bf16_f32 v143, v82, v83
	v_cvt_pk_bf16_f32 v144, v84, v85
	v_cvt_pk_bf16_f32 v145, v86, v87
	v_cvt_pk_bf16_f32 v146, v88, v89
	v_cvt_pk_bf16_f32 v147, v90, v91
	v_cvt_pk_bf16_f32 v148, v92, v93
	v_cvt_pk_bf16_f32 v149, v94, v95
	s_nop 1
	v_permlane32_swap_b32_e32 v179, v180
	v_permlane32_swap_b32_e32 v120, v122
	v_permlane32_swap_b32_e32 v121, v123
	v_permlane32_swap_b32_e32 v124, v126
	v_permlane32_swap_b32_e32 v125, v127
	v_permlane32_swap_b32_e32 v142, v144
	v_permlane32_swap_b32_e32 v143, v145
	v_permlane32_swap_b32_e32 v146, v148
	v_permlane32_swap_b32_e32 v147, v149
	ds_read_b128 v[64:67], v152 offset:32768
	ds_read_b128 v[172:175], v152 offset:45056
	v_mov_b64_e32 v[110:111], s[18:19]
	v_mov_b64_e32 v[108:109], s[16:17]
	v_mov_b64_e32 v[106:107], s[14:15]
	v_mov_b64_e32 v[104:105], s[12:13]
	v_mov_b64_e32 v[102:103], s[10:11]
	v_mov_b64_e32 v[100:101], s[8:9]
	v_mov_b64_e32 v[98:99], s[6:7]
	v_mov_b64_e32 v[96:97], s[4:5]
	s_waitcnt lgkmcnt(1)
	s_nop 0
	v_mfma_f32_32x32x16_bf16 v[80:95], v[64:67], v[138:141], v[96:111]
	s_waitcnt lgkmcnt(0)
	v_mfma_f32_32x32x16_bf16 v[64:79], v[172:175], v[138:141], v[96:111]
	s_nop 6
	ds_read_b128 v[96:99], v156 offset:32768
	ds_read_b128 v[100:103], v156 offset:45056
	s_waitcnt lgkmcnt(1)
	v_mfma_f32_32x32x16_bf16 v[80:95], v[96:99], v[134:137], v[80:95]
	s_waitcnt lgkmcnt(0)
	v_mfma_f32_32x32x16_bf16 v[64:79], v[100:103], v[134:137], v[64:79]
	ds_read_b128 v[96:99], v155 offset:32768
	ds_read_b128 v[100:103], v155 offset:45056
	s_waitcnt lgkmcnt(1)
	v_mfma_f32_32x32x16_bf16 v[80:95], v[96:99], v[130:133], v[80:95]
	s_waitcnt lgkmcnt(0)
	v_mfma_f32_32x32x16_bf16 v[64:79], v[100:103], v[130:133], v[64:79]
	ds_read_b128 v[96:99], v153 offset:32768
	ds_read_b128 v[100:103], v153 offset:45056
	ds_read_b128 v[104:107], v167
	s_waitcnt lgkmcnt(0)
	v_mfma_f32_32x32x16_bf16 v[80:95], v[96:99], v[104:107], v[80:95]
	v_mfma_f32_32x32x16_bf16 v[64:79], v[100:103], v[104:107], v[64:79]
	ds_read_b128 v[96:99], v152 offset:32896
	ds_read_b128 v[100:103], v152 offset:45184
	ds_read_b128 v[104:107], v167 offset:1024
	s_waitcnt lgkmcnt(0)
	v_mfma_f32_32x32x16_bf16 v[80:95], v[96:99], v[104:107], v[80:95]
	v_mfma_f32_32x32x16_bf16 v[64:79], v[100:103], v[104:107], v[64:79]
	ds_read_b128 v[96:99], v156 offset:32896
	ds_read_b128 v[100:103], v156 offset:45184
	ds_read_b128 v[104:107], v167 offset:2048
	s_waitcnt lgkmcnt(0)
	v_mfma_f32_32x32x16_bf16 v[80:95], v[96:99], v[104:107], v[80:95]
	v_mfma_f32_32x32x16_bf16 v[64:79], v[100:103], v[104:107], v[64:79]
	ds_read_b128 v[96:99], v155 offset:32896
	ds_read_b128 v[100:103], v155 offset:45184
	ds_read_b128 v[104:107], v167 offset:3072
	s_waitcnt lgkmcnt(0)
	v_mfma_f32_32x32x16_bf16 v[80:95], v[96:99], v[104:107], v[80:95]
	v_mfma_f32_32x32x16_bf16 v[64:79], v[100:103], v[104:107], v[64:79]
	ds_read_b128 v[96:99], v153 offset:32896
	ds_read_b128 v[100:103], v153 offset:45184
	ds_read_b128 v[104:107], v167 offset:4096
	s_waitcnt lgkmcnt(0)
	v_mfma_f32_32x32x16_bf16 v[80:95], v[96:99], v[104:107], v[80:95]
	v_mfma_f32_32x32x16_bf16 v[64:79], v[100:103], v[104:107], v[64:79]
	ds_read_b128 v[96:99], v152 offset:33024
	ds_read_b128 v[100:103], v152 offset:45312
	ds_read_b128 v[104:107], v167 offset:5120
	s_waitcnt lgkmcnt(0)
	v_mfma_f32_32x32x16_bf16 v[80:95], v[96:99], v[104:107], v[80:95]
	v_mfma_f32_32x32x16_bf16 v[64:79], v[100:103], v[104:107], v[64:79]
	ds_read_b128 v[96:99], v156 offset:33024
	ds_read_b128 v[100:103], v156 offset:45312
	ds_read_b128 v[104:107], v167 offset:6144
	s_waitcnt lgkmcnt(0)
	v_mfma_f32_32x32x16_bf16 v[80:95], v[96:99], v[104:107], v[80:95]
	v_mfma_f32_32x32x16_bf16 v[64:79], v[100:103], v[104:107], v[64:79]
	ds_read_b128 v[96:99], v155 offset:33024
	ds_read_b128 v[100:103], v155 offset:45312
	ds_read_b128 v[104:107], v167 offset:7168
	s_waitcnt lgkmcnt(0)
	v_mfma_f32_32x32x16_bf16 v[80:95], v[96:99], v[104:107], v[80:95]
	v_mfma_f32_32x32x16_bf16 v[64:79], v[100:103], v[104:107], v[64:79]
	ds_read_b128 v[96:99], v153 offset:33024
	ds_read_b128 v[100:103], v153 offset:45312
	ds_read_b128 v[104:107], v167 offset:8192
	s_waitcnt lgkmcnt(0)
	v_mfma_f32_32x32x16_bf16 v[80:95], v[96:99], v[104:107], v[80:95]
	v_mfma_f32_32x32x16_bf16 v[64:79], v[100:103], v[104:107], v[64:79]
	s_cmp_lt_u32 s3, s58
	s_cselect_b64 s[22:23], -1, 0
	s_cmp_ge_u32 s3, s58
	s_cselect_b64 s[20:21], -1, 0
	s_and_b64 vcc, exec, s[20:21]
	s_cbranch_vccnz .LBB0_373
	s_add_u32 s100, s72, s48
	s_addc_u32 s101, s73, s49
	v_readfirstlane_b32 s38, v168
	s_mov_b32 m0, s38
	s_nop 0
	global_load_lds_dwordx4 v235, s[100:101]
	s_add_i32 m0, s38, 0x2000
	s_nop 0
	global_load_lds_dwordx4 v236, s[100:101]
	s_add_i32 m0, s38, 0x4000
	s_nop 0
	global_load_lds_dwordx4 v237, s[100:101]
	s_add_u32 s100, s74, 0xd2bc000
	s_addc_u32 s101, s75, 0
	global_load_dwordx4 v[112:115], v232, s[100:101] offset:256
	s_add_u32 s100, s100, 0x8000
	s_addc_u32 s101, s101, 0
	global_load_dwordx4 v[116:119], v232, s[100:101] offset:256

; #define SBAR() __builtin_amdgcn_sched_barrier(0)
; #define QKT(P0, P1, BUF) qkt<DQK, QL>(P0, P1, shm + K_OFF + (BUF) * SHM_K, qr, qlds, kofs, negM)
;     ...
;   if (j < NT) {
;     SBAR();
;     if constexpr (ONEP) { finishSM(pA0, pA1, l_reg, pa0, pa1, pa2, pa3); SBAR(); QKT(pB0, pB1, 1); }
;     else { QKT(pB0, pB1, 1); finishSM(pA0, pA1, l_reg, pa0, pa1, pa2, pa3); }
;     SBAR();
;     pv_all<NCB>(o, vb0, pa0, pa1, pa2, pa3);
;     kb = TKEY(j);
;     partialSM<GM>(pB0, pB1, NEEDMASK(kb), kb, L, qpos, hi);
;     finishSM(pB0, pB1, l_reg, pa0, pa1, pa2, pa3); SBAR();
;     pv_all<NCB>(o, vb0 + SHM_V, pa0, pa1, pa2, pa3);
;   } else {
;     finishSM(pA0, pA1, l_reg, pa0, pa1, pa2, pa3); SBAR();
;     pv_all<NCB>(o, vb0, pa0, pa1, pa2, pa3);
;   }
.LBB0_379:
	v_mov_b32_e32 v232, 1
	v_mov_b32_e32 v235, 0x358637bd
	v_mov_b32_e32 v236, 0xc00
	v_mov_b32_e32 v237, 0x600
	v_exp_f32_e32 v179, v64
	v_exp_f32_e32 v180, v65
	v_exp_f32_e32 v181, v66
	v_exp_f32_e32 v182, v67
	v_exp_f32_e32 v183, v68
	v_exp_f32_e32 v184, v69
	v_exp_f32_e32 v185, v70
	v_exp_f32_e32 v186, v71
	v_exp_f32_e32 v162, v72
	v_exp_f32_e32 v163, v73
	v_exp_f32_e32 v164, v74
	v_exp_f32_e32 v165, v75
	v_exp_f32_e32 v166, v76
	v_exp_f32_e32 v168, v77
	v_exp_f32_e32 v169, v78
	v_exp_f32_e32 v170, v79
	v_add_f32_e32 v80, 0, v176
	s_mov_b64 s[22:23], -1
	s_and_b64 vcc, exec, s[20:21]
	v_add_f32_e32 v187, v178, v80
	s_cbranch_vccz .LBB0_381
	v_add_f32_e32 v64, v174, v187
	v_add_f32_e32 v64, v177, v64
	v_add_f32_e32 v64, v172, v64
	v_add_f32_e32 v64, v175, v64
	v_add_f32_e32 v64, v171, v64
	v_add_f32_e32 v64, v173, v64
	v_add_f32_e32 v64, v147, v64
	v_add_f32_e32 v64, v149, v64
	v_add_f32_e32 v64, v145, v64
	v_add_f32_e32 v64, v148, v64
	v_add_f32_e32 v64, v143, v64
	v_add_f32_e32 v64, v146, v64
	v_add_f32_e32 v64, v142, v64
	v_add_f32_e32 v64, v144, v64
	v_add_f32_e32 v64, v179, v64
	v_add_f32_e32 v64, v180, v64
	v_add_f32_e32 v64, v181, v64
	v_add_f32_e32 v64, v182, v64
	v_add_f32_e32 v64, v183, v64
	v_add_f32_e32 v64, v184, v64
	v_add_f32_e32 v64, v185, v64
	v_add_f32_e32 v64, v186, v64
	v_add_f32_e32 v64, v162, v64
	v_add_f32_e32 v64, v163, v64
	v_add_f32_e32 v64, v164, v64
	v_add_f32_e32 v64, v165, v64
	v_add_f32_e32 v64, v166, v64
	v_add_f32_e32 v64, v168, v64
	v_add_f32_e32 v64, v169, v64
	v_add_f32_e32 v64, v170, v64
	v_mov_b32_e32 v65, v64
	s_nop 1
	v_permlane32_swap_b32_e32 v64, v65
	v_add_f32_e32 v64, v64, v65
	v_add_f32_e32 v161, v150, v64
	v_cvt_pk_bf16_f32 v188, v176, v178
	v_cvt_pk_bf16_f32 v189, v174, v177
	v_cvt_pk_bf16_f32 v190, v172, v175
	v_cvt_pk_bf16_f32 v191, v171, v173
	v_cvt_pk_bf16_f32 v192, v147, v149
	v_cvt_pk_bf16_f32 v193, v145, v148
	v_cvt_pk_bf16_f32 v194, v143, v146
	v_cvt_pk_bf16_f32 v195, v142, v144
	v_cvt_pk_bf16_f32 v196, v179, v180
	v_cvt_pk_bf16_f32 v197, v181, v182
	v_cvt_pk_bf16_f32 v198, v183, v184
	v_cvt_pk_bf16_f32 v199, v185, v186
	v_cvt_pk_bf16_f32 v200, v162, v163
	v_cvt_pk_bf16_f32 v201, v164, v165
	v_cvt_pk_bf16_f32 v202, v166, v168
	v_cvt_pk_bf16_f32 v203, v169, v170
	s_nop 0
	v_permlane32_swap_b32_e32 v188, v190
	v_permlane32_swap_b32_e32 v189, v191
	v_permlane32_swap_b32_e32 v192, v194
	v_permlane32_swap_b32_e32 v193, v195
	v_permlane32_swap_b32_e32 v196, v198
	v_permlane32_swap_b32_e32 v197, v199
	v_permlane32_swap_b32_e32 v200, v202
	v_permlane32_swap_b32_e32 v201, v203
	ds_read_b64_tr_b16 v[80:81], v151 offset:0
	ds_read_b64_tr_b16 v[82:83], v151 offset:0x800
	ds_read_b64_tr_b16 v[84:85], v151 offset:0x1000
	ds_read_b64_tr_b16 v[86:87], v151 offset:0x1800
	ds_read_b64_tr_b16 v[88:89], v151 offset:0x2000
	ds_read_b64_tr_b16 v[90:91], v151 offset:0x2800
	ds_read_b64_tr_b16 v[92:93], v151 offset:0x3000
	ds_read_b64_tr_b16 v[94:95], v151 offset:0x3800
	s_nop 0
	s_waitcnt lgkmcnt(6)
	v_mfma_f32_32x32x16_bf16 v[64:79], v[188:191], v[80:83], v[0:15]
	ds_read_b64_tr_b16 v[96:97], v151 offset:0x200
	ds_read_b64_tr_b16 v[98:99], v151 offset:0xa00
	ds_read_b64_tr_b16 v[100:101], v151 offset:0x1200
	ds_read_b64_tr_b16 v[102:103], v151 offset:0x1a00
	ds_read_b64_tr_b16 v[104:105], v151 offset:0x2200
	ds_read_b64_tr_b16 v[106:107], v151 offset:0x2a00
	ds_read_b64_tr_b16 v[108:109], v151 offset:0x3200
	s_waitcnt lgkmcnt(11)
	v_mfma_f32_32x32x16_bf16 v[64:79], v[192:195], v[84:87], v[64:79]
	ds_read_b64_tr_b16 v[110:111], v151 offset:0x3a00
	s_waitcnt lgkmcnt(10)
	v_mfma_f32_32x32x16_bf16 v[64:79], v[196:199], v[88:91], v[64:79]
	s_waitcnt lgkmcnt(8)
	v_mfma_f32_32x32x16_bf16 v[64:79], v[200:203], v[92:95], v[64:79]
	s_waitcnt lgkmcnt(6)
	v_mfma_f32_32x32x16_bf16 v[80:95], v[188:191], v[96:99], v[16:31]
	ds_read_b64_tr_b16 v[112:113], v151 offset:0x400
	ds_read_b64_tr_b16 v[114:115], v151 offset:0xc00
	ds_read_b64_tr_b16 v[116:117], v151 offset:0x1400
	ds_read_b64_tr_b16 v[118:119], v151 offset:0x1c00
	ds_read_b64_tr_b16 v[120:121], v151 offset:0x2400
	ds_read_b64_tr_b16 v[122:123], v151 offset:0x2c00
	ds_read_b64_tr_b16 v[124:125], v151 offset:0x3400
	s_waitcnt lgkmcnt(11)
	v_mfma_f32_32x32x16_bf16 v[80:95], v[192:195], v[100:103], v[80:95]
	ds_read_b64_tr_b16 v[126:127], v151 offset:0x3c00
	s_waitcnt lgkmcnt(10)
	v_mfma_f32_32x32x16_bf16 v[80:95], v[196:199], v[104:107], v[80:95]
	s_waitcnt lgkmcnt(8)
	v_mfma_f32_32x32x16_bf16 v[80:95], v[200:203], v[108:111], v[80:95]
	s_waitcnt lgkmcnt(6)
	v_mfma_f32_32x32x16_bf16 v[96:111], v[188:191], v[112:115], v[32:47]
	ds_read_b64_tr_b16 v[204:205], v151 offset:0x600
	ds_read_b64_tr_b16 v[206:207], v151 offset:0xe00
	ds_read_b64_tr_b16 v[208:209], v151 offset:0x1600
	ds_read_b64_tr_b16 v[210:211], v151 offset:0x1e00
	ds_read_b64_tr_b16 v[212:213], v151 offset:0x2600
	ds_read_b64_tr_b16 v[214:215], v151 offset:0x2e00
	ds_read_b64_tr_b16 v[216:217], v151 offset:0x3600
	s_waitcnt lgkmcnt(11)
	v_mfma_f32_32x32x16_bf16 v[96:111], v[192:195], v[116:119], v[96:111]
	ds_read_b64_tr_b16 v[218:219], v151 offset:0x3e00
	s_waitcnt lgkmcnt(10)
	v_mfma_f32_32x32x16_bf16 v[96:111], v[196:199], v[120:123], v[96:111]
	s_waitcnt lgkmcnt(8)
	v_mfma_f32_32x32x16_bf16 v[96:111], v[200:203], v[124:127], v[96:111]
	s_waitcnt lgkmcnt(6)
	v_mfma_f32_32x32x16_bf16 v[112:127], v[188:191], v[204:207], v[48:63]
	s_mov_b64 s[22:23], 0
	s_waitcnt lgkmcnt(4)
	v_mfma_f32_32x32x16_bf16 v[112:127], v[192:195], v[208:211], v[112:127]
	s_waitcnt lgkmcnt(2)
	v_mfma_f32_32x32x16_bf16 v[112:127], v[196:199], v[212:215], v[112:127]
	s_waitcnt lgkmcnt(0)
	v_mfma_f32_32x32x16_bf16 v[112:127], v[200:203], v[216:219], v[112:127]
